# combined: K-loop DMA rebalance (FFN-up, W_in) + hoisted rss loads in FFN-up/W_in epilogues + hoisted norm-gain loads in prep transposes + software-pipelined branch-GEMM epilogue
# speedup vs baseline: 1.0073x; 1.0054x over previous
; __device__ __forceinline__ unsigned pk2(float lo, float hi) { const f32v2_t v = {lo, hi}; const bf16v2_t b = __builtin_convertvector(v, bf16v2_t); return __builtin_bit_cast(unsigned, b); }
; __device__ __forceinline__ float bflo(unsigned w) { return __uint_as_float(w << 16); }
; __device__ __forceinline__ float bfhi(unsigned w) { return __uint_as_float(w & 0xffff0000u); }
;     __device__ __forceinline__ void operator()(AccRef acc, const Unit& u, int wr, int wc, int fr, int fq) const {
;         const int row0 = u.pm * BM + wr * 64 + fr, col0 = u.pn * BM + wc * 32 + 8 * fq;
;         const bf16_t* G = G0 + u.seg * 2048; const bool accum = u.seg > 0;
; #pragma unroll
;         for (int ai = 0; ai < 2; ++ai)
; #pragma unroll
;             for (int m = 0; m < 4; ++m) {
;                 const int row = row0 + ai * HALF + m * 16;
; #pragma unroll
;                 for (int bj = 0; bj < 2; ++bj) {
;                     const int col = col0 + bj * HALF;
;                     const u32x4 gv = *(const u32x4*)(G + (size_t)row * ZW + col);
;                     u32x4 pv = (u32x4){0u, 0u, 0u, 0u};
;                     if (accum) pv = *(const u32x4*)(MB + (size_t)row * DM + col);
;                     const f32x4 a0 = acc[ai][bj][m][0], a1 = acc[ai][bj][m][1];
;                     u32x4 o;
;                     o.x = pk2(bflo(pv.x) + bflo(gv.x) * a0[0], bfhi(pv.x) + bfhi(gv.x) * a0[1]);
;                     o.y = pk2(bflo(pv.y) + bflo(gv.y) * a0[2], bfhi(pv.y) + bfhi(gv.y) * a0[3]);
;                     o.z = pk2(bflo(pv.z) + bflo(gv.z) * a1[0], bfhi(pv.z) + bfhi(gv.z) * a1[1]);
;                     o.w = pk2(bflo(pv.w) + bflo(gv.w) * a1[2], bfhi(pv.w) + bfhi(gv.w) * a1[3]);
;                     *(u32x4*)(MB + (size_t)row * DM + col) = o;
.LBB0_144:
	s_lshl_b32 s4, s60, 12
	v_readlane_b32 s8, v250, 20
	s_add_u32 s52, s8, s4
	v_readlane_b32 s4, v250, 21
	s_addc_u32 s53, s4, 0
	v_lshl_or_b32 v164, s64, 8, v181
	v_lshl_add_u32 v166, s63, 8, v172
	v_mov_b64_e32 v[128:129], s[52:53]
	v_mad_i64_i32 v[128:129], s[22:23], v166, s35, v[128:129]
	v_ashrrev_i32_e32 v165, 31, v164
	v_lshl_add_u64 v[170:171], v[164:165], 1, v[128:129]
	v_ashrrev_i32_e32 v167, 31, v166
	v_lshlrev_b64 v[132:133], 12, v[166:167]
	s_cmp_lg_u32 s60, 0
	v_lshl_add_u64 v[132:133], s[72:73], 0, v[132:133]
	s_cselect_b64 s[22:23], -1, 0
	s_cmp_eq_u32 s60, 0
	v_lshl_add_u64 v[168:169], v[164:165], 1, v[132:133]
	s_mov_b32 s101, 0
	s_cbranch_scc1 .Lbrn_noacc
	s_mov_b32 s100, 0x0
	v_lshl_add_u64 v[132:133], v[170:171], 0, s[100:101]
	global_load_dwordx4 v[194:197], v[132:133], off
	s_mov_b32 s100, 0x0
	v_lshl_add_u64 v[134:135], v[168:169], 0, s[100:101]
	global_load_dwordx4 v[198:201], v[134:135], off
	s_mov_b32 s100, 0x0
	v_lshl_add_u64 v[132:133], v[170:171], 0, s[100:101]
	global_load_dwordx4 v[202:205], v[132:133], off offset:256
	s_mov_b32 s100, 0x0
	v_lshl_add_u64 v[134:135], v[168:169], 0, s[100:101]
	global_load_dwordx4 v[206:209], v[134:135], off offset:256
	s_mov_b32 s100, 0x50000
	v_lshl_add_u64 v[132:133], v[170:171], 0, s[100:101]
	global_load_dwordx4 v[210:213], v[132:133], off
	s_mov_b32 s100, 0x10000
	v_lshl_add_u64 v[134:135], v[168:169], 0, s[100:101]
	global_load_dwordx4 v[214:217], v[134:135], off
	s_mov_b32 s100, 0x50000
	v_lshl_add_u64 v[132:133], v[170:171], 0, s[100:101]
	global_load_dwordx4 v[218:221], v[132:133], off offset:256
	s_mov_b32 s100, 0x10000
	v_lshl_add_u64 v[134:135], v[168:169], 0, s[100:101]
	global_load_dwordx4 v[222:225], v[134:135], off offset:256
	s_mov_b32 s100, 0xa0000
	v_lshl_add_u64 v[132:133], v[170:171], 0, s[100:101]
	global_load_dwordx4 v[226:229], v[132:133], off
	s_mov_b32 s100, 0x20000
	v_lshl_add_u64 v[134:135], v[168:169], 0, s[100:101]
	global_load_dwordx4 v[230:233], v[134:135], off
	s_mov_b32 s100, 0xa0000
	v_lshl_add_u64 v[132:133], v[170:171], 0, s[100:101]
	global_load_dwordx4 v[184:187], v[132:133], off offset:256
	s_mov_b32 s100, 0x20000
	v_lshl_add_u64 v[134:135], v[168:169], 0, s[100:101]
	global_load_dwordx4 v[188:191], v[134:135], off offset:256
	s_waitcnt vmcnt(10)
	v_lshlrev_b32_e32 v128, 16, v194
	v_and_b32_e32 v129, 0xffff0000, v194
	v_lshlrev_b32_e32 v130, 16, v198
	v_and_b32_e32 v131, 0xffff0000, v198
	v_pk_fma_f32 v[124:125], v[124:125], v[128:129], v[130:131]
	v_lshlrev_b32_e32 v128, 16, v195
	v_and_b32_e32 v129, 0xffff0000, v195
	v_lshlrev_b32_e32 v130, 16, v199
	v_and_b32_e32 v131, 0xffff0000, v199
	v_pk_fma_f32 v[126:127], v[126:127], v[128:129], v[130:131]
	v_lshlrev_b32_e32 v128, 16, v196
	v_and_b32_e32 v129, 0xffff0000, v196
	v_lshlrev_b32_e32 v130, 16, v200
	v_and_b32_e32 v131, 0xffff0000, v200
	v_pk_fma_f32 v[120:121], v[120:121], v[128:129], v[130:131]
	v_lshlrev_b32_e32 v128, 16, v197
	v_and_b32_e32 v129, 0xffff0000, v197
	v_lshlrev_b32_e32 v130, 16, v201
	v_and_b32_e32 v131, 0xffff0000, v201
	v_pk_fma_f32 v[122:123], v[122:123], v[128:129], v[130:131]
	v_cvt_pk_bf16_f32 v124, v124, v125
	v_cvt_pk_bf16_f32 v125, v126, v127
	v_cvt_pk_bf16_f32 v126, v120, v121
	v_cvt_pk_bf16_f32 v127, v122, v123
	s_mov_b32 s100, 0x0
	v_lshl_add_u64 v[164:165], v[168:169], 0, s[100:101]
	global_store_dwordx4 v[164:165], v[124:127], off
	s_mov_b32 s100, 0xf0000
	v_lshl_add_u64 v[132:133], v[170:171], 0, s[100:101]
	global_load_dwordx4 v[194:197], v[132:133], off
	s_mov_b32 s100, 0x30000
	v_lshl_add_u64 v[134:135], v[168:169], 0, s[100:101]
	global_load_dwordx4 v[198:201], v[134:135], off
	s_waitcnt vmcnt(11)
	v_lshlrev_b32_e32 v128, 16, v202
	v_and_b32_e32 v129, 0xffff0000, v202
	v_lshlrev_b32_e32 v130, 16, v206
	v_and_b32_e32 v131, 0xffff0000, v206
	v_pk_fma_f32 v[116:117], v[116:117], v[128:129], v[130:131]
	v_lshlrev_b32_e32 v128, 16, v203
	v_and_b32_e32 v129, 0xffff0000, v203
	v_lshlrev_b32_e32 v130, 16, v207
	v_and_b32_e32 v131, 0xffff0000, v207
	v_pk_fma_f32 v[118:119], v[118:119], v[128:129], v[130:131]
	v_lshlrev_b32_e32 v128, 16, v204
	v_and_b32_e32 v129, 0xffff0000, v204
	v_lshlrev_b32_e32 v130, 16, v208
	v_and_b32_e32 v131, 0xffff0000, v208
	v_pk_fma_f32 v[112:113], v[112:113], v[128:129], v[130:131]
	v_lshlrev_b32_e32 v128, 16, v205
	v_and_b32_e32 v129, 0xffff0000, v205
	v_lshlrev_b32_e32 v130, 16, v209
	v_and_b32_e32 v131, 0xffff0000, v209
	v_pk_fma_f32 v[114:115], v[114:115], v[128:129], v[130:131]
	v_cvt_pk_bf16_f32 v116, v116, v117
	v_cvt_pk_bf16_f32 v117, v118, v119
	v_cvt_pk_bf16_f32 v118, v112, v113
	v_cvt_pk_bf16_f32 v119, v114, v115
	s_mov_b32 s100, 0x0
	v_lshl_add_u64 v[164:165], v[168:169], 0, s[100:101]
	global_store_dwordx4 v[164:165], v[116:119], off offset:256
	s_mov_b32 s100, 0xf0000
	v_lshl_add_u64 v[132:133], v[170:171], 0, s[100:101]
	global_load_dwordx4 v[202:205], v[132:133], off offset:256
	s_mov_b32 s100, 0x30000
	v_lshl_add_u64 v[134:135], v[168:169], 0, s[100:101]
	global_load_dwordx4 v[206:209], v[134:135], off offset:256
	s_waitcnt vmcnt(12)
; __device__ __forceinline__ unsigned pk2(float lo, float hi) { const f32v2_t v = {lo, hi}; const bf16v2_t b = __builtin_convertvector(v, bf16v2_t); return __builtin_bit_cast(unsigned, b); }
; __device__ __forceinline__ float bflo(unsigned w) { return __uint_as_float(w << 16); }
; __device__ __forceinline__ float bfhi(unsigned w) { return __uint_as_float(w & 0xffff0000u); }
;     __device__ __forceinline__ void operator()(AccRef acc, const Unit& u, int wr, int wc, int fr, int fq) const {
;     ...
; #pragma unroll
;                 for (int bj = 0; bj < 2; ++bj) {
;                     const int col = col0 + bj * HALF;
;                     const u32x4 gv = *(const u32x4*)(G + (size_t)row * ZW + col);
;                     u32x4 pv = (u32x4){0u, 0u, 0u, 0u};
;                     if (accum) pv = *(const u32x4*)(MB + (size_t)row * DM + col);
;                     const f32x4 a0 = acc[ai][bj][m][0], a1 = acc[ai][bj][m][1];
;                     u32x4 o;
;                     o.x = pk2(bflo(pv.x) + bflo(gv.x) * a0[0], bfhi(pv.x) + bfhi(gv.x) * a0[1]);
;                     o.y = pk2(bflo(pv.y) + bflo(gv.y) * a0[2], bfhi(pv.y) + bfhi(gv.y) * a0[3]);
;                     o.z = pk2(bflo(pv.z) + bflo(gv.z) * a1[0], bfhi(pv.z) + bfhi(gv.z) * a1[1]);
;                     o.w = pk2(bflo(pv.w) + bflo(gv.w) * a1[2], bfhi(pv.w) + bfhi(gv.w) * a1[3]);
;                     *(u32x4*)(MB + (size_t)row * DM + col) = o;
	v_lshlrev_b32_e32 v128, 16, v210
	v_and_b32_e32 v129, 0xffff0000, v210
	v_lshlrev_b32_e32 v130, 16, v214
	v_and_b32_e32 v131, 0xffff0000, v214
	v_pk_fma_f32 v[108:109], v[108:109], v[128:129], v[130:131]
	v_lshlrev_b32_e32 v128, 16, v211
	v_and_b32_e32 v129, 0xffff0000, v211
	v_lshlrev_b32_e32 v130, 16, v215
	v_and_b32_e32 v131, 0xffff0000, v215
	v_pk_fma_f32 v[110:111], v[110:111], v[128:129], v[130:131]
	v_lshlrev_b32_e32 v128, 16, v212
	v_and_b32_e32 v129, 0xffff0000, v212
	v_lshlrev_b32_e32 v130, 16, v216
	v_and_b32_e32 v131, 0xffff0000, v216
	v_pk_fma_f32 v[104:105], v[104:105], v[128:129], v[130:131]
	v_lshlrev_b32_e32 v128, 16, v213
	v_and_b32_e32 v129, 0xffff0000, v213
	v_lshlrev_b32_e32 v130, 16, v217
	v_and_b32_e32 v131, 0xffff0000, v217
	v_pk_fma_f32 v[106:107], v[106:107], v[128:129], v[130:131]
	v_cvt_pk_bf16_f32 v108, v108, v109
	v_cvt_pk_bf16_f32 v109, v110, v111
	v_cvt_pk_bf16_f32 v110, v104, v105
	v_cvt_pk_bf16_f32 v111, v106, v107
	s_mov_b32 s100, 0x10000
	v_lshl_add_u64 v[164:165], v[168:169], 0, s[100:101]
	global_store_dwordx4 v[164:165], v[108:111], off
	s_mov_b32 s100, 0x280000
	v_lshl_add_u64 v[132:133], v[170:171], 0, s[100:101]
	global_load_dwordx4 v[210:213], v[132:133], off
	s_mov_b32 s100, 0x80000
	v_lshl_add_u64 v[134:135], v[168:169], 0, s[100:101]
	global_load_dwordx4 v[214:217], v[134:135], off
	s_waitcnt vmcnt(13)
	v_lshlrev_b32_e32 v128, 16, v218
	v_and_b32_e32 v129, 0xffff0000, v218
	v_lshlrev_b32_e32 v130, 16, v222
	v_and_b32_e32 v131, 0xffff0000, v222
	v_pk_fma_f32 v[100:101], v[100:101], v[128:129], v[130:131]
	v_lshlrev_b32_e32 v128, 16, v219
	v_and_b32_e32 v129, 0xffff0000, v219
	v_lshlrev_b32_e32 v130, 16, v223
	v_and_b32_e32 v131, 0xffff0000, v223
	v_pk_fma_f32 v[102:103], v[102:103], v[128:129], v[130:131]
	v_lshlrev_b32_e32 v128, 16, v220
	v_and_b32_e32 v129, 0xffff0000, v220
	v_lshlrev_b32_e32 v130, 16, v224
	v_and_b32_e32 v131, 0xffff0000, v224
	v_pk_fma_f32 v[96:97], v[96:97], v[128:129], v[130:131]
	v_lshlrev_b32_e32 v128, 16, v221
	v_and_b32_e32 v129, 0xffff0000, v221
	v_lshlrev_b32_e32 v130, 16, v225
	v_and_b32_e32 v131, 0xffff0000, v225
	v_pk_fma_f32 v[98:99], v[98:99], v[128:129], v[130:131]
	v_cvt_pk_bf16_f32 v100, v100, v101
	v_cvt_pk_bf16_f32 v101, v102, v103
	v_cvt_pk_bf16_f32 v102, v96, v97
	v_cvt_pk_bf16_f32 v103, v98, v99
	s_mov_b32 s100, 0x10000
	v_lshl_add_u64 v[164:165], v[168:169], 0, s[100:101]
	global_store_dwordx4 v[164:165], v[100:103], off offset:256
	s_mov_b32 s100, 0x280000
	v_lshl_add_u64 v[132:133], v[170:171], 0, s[100:101]
	global_load_dwordx4 v[218:221], v[132:133], off offset:256
	s_mov_b32 s100, 0x80000
	v_lshl_add_u64 v[134:135], v[168:169], 0, s[100:101]
	global_load_dwordx4 v[222:225], v[134:135], off offset:256
	s_waitcnt vmcnt(14)
	v_lshlrev_b32_e32 v128, 16, v226
	v_and_b32_e32 v129, 0xffff0000, v226
	v_lshlrev_b32_e32 v130, 16, v230
	v_and_b32_e32 v131, 0xffff0000, v230
	v_pk_fma_f32 v[92:93], v[92:93], v[128:129], v[130:131]
	v_lshlrev_b32_e32 v128, 16, v227
	v_and_b32_e32 v129, 0xffff0000, v227
	v_lshlrev_b32_e32 v130, 16, v231
	v_and_b32_e32 v131, 0xffff0000, v231
	v_pk_fma_f32 v[94:95], v[94:95], v[128:129], v[130:131]
	v_lshlrev_b32_e32 v128, 16, v228
	v_and_b32_e32 v129, 0xffff0000, v228
	v_lshlrev_b32_e32 v130, 16, v232
	v_and_b32_e32 v131, 0xffff0000, v232
	v_pk_fma_f32 v[88:89], v[88:89], v[128:129], v[130:131]
	v_lshlrev_b32_e32 v128, 16, v229
	v_and_b32_e32 v129, 0xffff0000, v229
	v_lshlrev_b32_e32 v130, 16, v233
	v_and_b32_e32 v131, 0xffff0000, v233
	v_pk_fma_f32 v[90:91], v[90:91], v[128:129], v[130:131]
	v_cvt_pk_bf16_f32 v92, v92, v93
	v_cvt_pk_bf16_f32 v93, v94, v95
	v_cvt_pk_bf16_f32 v94, v88, v89
	v_cvt_pk_bf16_f32 v95, v90, v91
	s_mov_b32 s100, 0x20000
	v_lshl_add_u64 v[164:165], v[168:169], 0, s[100:101]
	global_store_dwordx4 v[164:165], v[92:95], off
	s_mov_b32 s100, 0x2d0000
	v_lshl_add_u64 v[132:133], v[170:171], 0, s[100:101]
	global_load_dwordx4 v[226:229], v[132:133], off
	s_mov_b32 s100, 0x90000
	v_lshl_add_u64 v[134:135], v[168:169], 0, s[100:101]
	global_load_dwordx4 v[230:233], v[134:135], off
	s_waitcnt vmcnt(15)
	v_lshlrev_b32_e32 v128, 16, v184
	v_and_b32_e32 v129, 0xffff0000, v184
	v_lshlrev_b32_e32 v130, 16, v188
	v_and_b32_e32 v131, 0xffff0000, v188
	v_pk_fma_f32 v[84:85], v[84:85], v[128:129], v[130:131]
	v_lshlrev_b32_e32 v128, 16, v185
	v_and_b32_e32 v129, 0xffff0000, v185
	v_lshlrev_b32_e32 v130, 16, v189
	v_and_b32_e32 v131, 0xffff0000, v189
	v_pk_fma_f32 v[86:87], v[86:87], v[128:129], v[130:131]
	v_lshlrev_b32_e32 v128, 16, v186
	v_and_b32_e32 v129, 0xffff0000, v186
	v_lshlrev_b32_e32 v130, 16, v190
	v_and_b32_e32 v131, 0xffff0000, v190
	v_pk_fma_f32 v[80:81], v[80:81], v[128:129], v[130:131]
	v_lshlrev_b32_e32 v128, 16, v187
	v_and_b32_e32 v129, 0xffff0000, v187
	v_lshlrev_b32_e32 v130, 16, v191
	v_and_b32_e32 v131, 0xffff0000, v191
	v_pk_fma_f32 v[82:83], v[82:83], v[128:129], v[130:131]
	v_cvt_pk_bf16_f32 v84, v84, v85
	v_cvt_pk_bf16_f32 v85, v86, v87
	v_cvt_pk_bf16_f32 v86, v80, v81
	v_cvt_pk_bf16_f32 v87, v82, v83
	s_mov_b32 s100, 0x20000
	v_lshl_add_u64 v[164:165], v[168:169], 0, s[100:101]
	global_store_dwordx4 v[164:165], v[84:87], off offset:256
	s_mov_b32 s100, 0x2d0000
	v_lshl_add_u64 v[132:133], v[170:171], 0, s[100:101]
	global_load_dwordx4 v[184:187], v[132:133], off offset:256
	s_mov_b32 s100, 0x90000
	v_lshl_add_u64 v[134:135], v[168:169], 0, s[100:101]
	global_load_dwordx4 v[188:191], v[134:135], off offset:256
	s_waitcnt vmcnt(15)
; __device__ __forceinline__ unsigned pk2(float lo, float hi) { const f32v2_t v = {lo, hi}; const bf16v2_t b = __builtin_convertvector(v, bf16v2_t); return __builtin_bit_cast(unsigned, b); }
; __device__ __forceinline__ float bflo(unsigned w) { return __uint_as_float(w << 16); }
; __device__ __forceinline__ float bfhi(unsigned w) { return __uint_as_float(w & 0xffff0000u); }
;     __device__ __forceinline__ void operator()(AccRef acc, const Unit& u, int wr, int wc, int fr, int fq) const {
;     ...
; #pragma unroll
;                 for (int bj = 0; bj < 2; ++bj) {
;                     const int col = col0 + bj * HALF;
;                     const u32x4 gv = *(const u32x4*)(G + (size_t)row * ZW + col);
;                     u32x4 pv = (u32x4){0u, 0u, 0u, 0u};
;                     if (accum) pv = *(const u32x4*)(MB + (size_t)row * DM + col);
;                     const f32x4 a0 = acc[ai][bj][m][0], a1 = acc[ai][bj][m][1];
;                     u32x4 o;
;                     o.x = pk2(bflo(pv.x) + bflo(gv.x) * a0[0], bfhi(pv.x) + bfhi(gv.x) * a0[1]);
;                     o.y = pk2(bflo(pv.y) + bflo(gv.y) * a0[2], bfhi(pv.y) + bfhi(gv.y) * a0[3]);
;                     o.z = pk2(bflo(pv.z) + bflo(gv.z) * a1[0], bfhi(pv.z) + bfhi(gv.z) * a1[1]);
;                     o.w = pk2(bflo(pv.w) + bflo(gv.w) * a1[2], bfhi(pv.w) + bfhi(gv.w) * a1[3]);
;                     *(u32x4*)(MB + (size_t)row * DM + col) = o;
	v_lshlrev_b32_e32 v128, 16, v194
	v_and_b32_e32 v129, 0xffff0000, v194
	v_lshlrev_b32_e32 v130, 16, v198
	v_and_b32_e32 v131, 0xffff0000, v198
	v_pk_fma_f32 v[76:77], v[76:77], v[128:129], v[130:131]
	v_lshlrev_b32_e32 v128, 16, v195
	v_and_b32_e32 v129, 0xffff0000, v195
	v_lshlrev_b32_e32 v130, 16, v199
	v_and_b32_e32 v131, 0xffff0000, v199
	v_pk_fma_f32 v[78:79], v[78:79], v[128:129], v[130:131]
	v_lshlrev_b32_e32 v128, 16, v196
	v_and_b32_e32 v129, 0xffff0000, v196
	v_lshlrev_b32_e32 v130, 16, v200
	v_and_b32_e32 v131, 0xffff0000, v200
	v_pk_fma_f32 v[72:73], v[72:73], v[128:129], v[130:131]
	v_lshlrev_b32_e32 v128, 16, v197
	v_and_b32_e32 v129, 0xffff0000, v197
	v_lshlrev_b32_e32 v130, 16, v201
	v_and_b32_e32 v131, 0xffff0000, v201
	v_pk_fma_f32 v[74:75], v[74:75], v[128:129], v[130:131]
	v_cvt_pk_bf16_f32 v76, v76, v77
	v_cvt_pk_bf16_f32 v77, v78, v79
	v_cvt_pk_bf16_f32 v78, v72, v73
	v_cvt_pk_bf16_f32 v79, v74, v75
	s_mov_b32 s100, 0x30000
	v_lshl_add_u64 v[164:165], v[168:169], 0, s[100:101]
	global_store_dwordx4 v[164:165], v[76:79], off
	s_mov_b32 s100, 0x320000
	v_lshl_add_u64 v[132:133], v[170:171], 0, s[100:101]
	global_load_dwordx4 v[194:197], v[132:133], off
	s_mov_b32 s100, 0xa0000
	v_lshl_add_u64 v[134:135], v[168:169], 0, s[100:101]
	global_load_dwordx4 v[198:201], v[134:135], off
	s_waitcnt vmcnt(15)
	v_lshlrev_b32_e32 v128, 16, v202
	v_and_b32_e32 v129, 0xffff0000, v202
	v_lshlrev_b32_e32 v130, 16, v206
	v_and_b32_e32 v131, 0xffff0000, v206
	v_pk_fma_f32 v[68:69], v[68:69], v[128:129], v[130:131]
	v_lshlrev_b32_e32 v128, 16, v203
	v_and_b32_e32 v129, 0xffff0000, v203
	v_lshlrev_b32_e32 v130, 16, v207
	v_and_b32_e32 v131, 0xffff0000, v207
	v_pk_fma_f32 v[70:71], v[70:71], v[128:129], v[130:131]
	v_lshlrev_b32_e32 v128, 16, v204
	v_and_b32_e32 v129, 0xffff0000, v204
	v_lshlrev_b32_e32 v130, 16, v208
	v_and_b32_e32 v131, 0xffff0000, v208
	v_pk_fma_f32 v[64:65], v[64:65], v[128:129], v[130:131]
	v_lshlrev_b32_e32 v128, 16, v205
	v_and_b32_e32 v129, 0xffff0000, v205
	v_lshlrev_b32_e32 v130, 16, v209
	v_and_b32_e32 v131, 0xffff0000, v209
	v_pk_fma_f32 v[66:67], v[66:67], v[128:129], v[130:131]
	v_cvt_pk_bf16_f32 v68, v68, v69
	v_cvt_pk_bf16_f32 v69, v70, v71
	v_cvt_pk_bf16_f32 v70, v64, v65
	v_cvt_pk_bf16_f32 v71, v66, v67
	s_mov_b32 s100, 0x30000
	v_lshl_add_u64 v[164:165], v[168:169], 0, s[100:101]
	global_store_dwordx4 v[164:165], v[68:71], off offset:256
	s_mov_b32 s100, 0x320000
	v_lshl_add_u64 v[132:133], v[170:171], 0, s[100:101]
	global_load_dwordx4 v[202:205], v[132:133], off offset:256
	s_mov_b32 s100, 0xa0000
	v_lshl_add_u64 v[134:135], v[168:169], 0, s[100:101]
	global_load_dwordx4 v[206:209], v[134:135], off offset:256
	s_waitcnt vmcnt(15)
	v_lshlrev_b32_e32 v128, 16, v210
	v_and_b32_e32 v129, 0xffff0000, v210
	v_lshlrev_b32_e32 v130, 16, v214
	v_and_b32_e32 v131, 0xffff0000, v214
	v_pk_fma_f32 v[60:61], v[60:61], v[128:129], v[130:131]
	v_lshlrev_b32_e32 v128, 16, v211
	v_and_b32_e32 v129, 0xffff0000, v211
	v_lshlrev_b32_e32 v130, 16, v215
	v_and_b32_e32 v131, 0xffff0000, v215
	v_pk_fma_f32 v[62:63], v[62:63], v[128:129], v[130:131]
	v_lshlrev_b32_e32 v128, 16, v212
	v_and_b32_e32 v129, 0xffff0000, v212
	v_lshlrev_b32_e32 v130, 16, v216
	v_and_b32_e32 v131, 0xffff0000, v216
	v_pk_fma_f32 v[56:57], v[56:57], v[128:129], v[130:131]
	v_lshlrev_b32_e32 v128, 16, v213
	v_and_b32_e32 v129, 0xffff0000, v213
	v_lshlrev_b32_e32 v130, 16, v217
	v_and_b32_e32 v131, 0xffff0000, v217
	v_pk_fma_f32 v[58:59], v[58:59], v[128:129], v[130:131]
	v_cvt_pk_bf16_f32 v60, v60, v61
	v_cvt_pk_bf16_f32 v61, v62, v63
	v_cvt_pk_bf16_f32 v62, v56, v57
	v_cvt_pk_bf16_f32 v63, v58, v59
	s_mov_b32 s100, 0x80000
	v_lshl_add_u64 v[164:165], v[168:169], 0, s[100:101]
	global_store_dwordx4 v[164:165], v[60:63], off
	s_mov_b32 s100, 0x370000
	v_lshl_add_u64 v[132:133], v[170:171], 0, s[100:101]
	global_load_dwordx4 v[210:213], v[132:133], off
	s_mov_b32 s100, 0xb0000
	v_lshl_add_u64 v[134:135], v[168:169], 0, s[100:101]
	global_load_dwordx4 v[214:217], v[134:135], off
	s_waitcnt vmcnt(15)
	v_lshlrev_b32_e32 v128, 16, v218
	v_and_b32_e32 v129, 0xffff0000, v218
	v_lshlrev_b32_e32 v130, 16, v222
	v_and_b32_e32 v131, 0xffff0000, v222
	v_pk_fma_f32 v[52:53], v[52:53], v[128:129], v[130:131]
	v_lshlrev_b32_e32 v128, 16, v219
	v_and_b32_e32 v129, 0xffff0000, v219
	v_lshlrev_b32_e32 v130, 16, v223
	v_and_b32_e32 v131, 0xffff0000, v223
	v_pk_fma_f32 v[54:55], v[54:55], v[128:129], v[130:131]
	v_lshlrev_b32_e32 v128, 16, v220
	v_and_b32_e32 v129, 0xffff0000, v220
	v_lshlrev_b32_e32 v130, 16, v224
	v_and_b32_e32 v131, 0xffff0000, v224
	v_pk_fma_f32 v[48:49], v[48:49], v[128:129], v[130:131]
	v_lshlrev_b32_e32 v128, 16, v221
	v_and_b32_e32 v129, 0xffff0000, v221
	v_lshlrev_b32_e32 v130, 16, v225
	v_and_b32_e32 v131, 0xffff0000, v225
	v_pk_fma_f32 v[50:51], v[50:51], v[128:129], v[130:131]
	v_cvt_pk_bf16_f32 v52, v52, v53
	v_cvt_pk_bf16_f32 v53, v54, v55
	v_cvt_pk_bf16_f32 v54, v48, v49
	v_cvt_pk_bf16_f32 v55, v50, v51
	s_mov_b32 s100, 0x80000
	v_lshl_add_u64 v[164:165], v[168:169], 0, s[100:101]
	global_store_dwordx4 v[164:165], v[52:55], off offset:256
	s_mov_b32 s100, 0x370000
	v_lshl_add_u64 v[132:133], v[170:171], 0, s[100:101]
	global_load_dwordx4 v[218:221], v[132:133], off offset:256
	s_mov_b32 s100, 0xb0000
	v_lshl_add_u64 v[134:135], v[168:169], 0, s[100:101]
	global_load_dwordx4 v[222:225], v[134:135], off offset:256
	s_waitcnt vmcnt(15)
; __device__ __forceinline__ unsigned pk2(float lo, float hi) { const f32v2_t v = {lo, hi}; const bf16v2_t b = __builtin_convertvector(v, bf16v2_t); return __builtin_bit_cast(unsigned, b); }
; __device__ __forceinline__ float bflo(unsigned w) { return __uint_as_float(w << 16); }
; __device__ __forceinline__ float bfhi(unsigned w) { return __uint_as_float(w & 0xffff0000u); }
;     __device__ __forceinline__ void operator()(AccRef acc, const Unit& u, int wr, int wc, int fr, int fq) const {
;     ...
; #pragma unroll
;                 for (int bj = 0; bj < 2; ++bj) {
;                     const int col = col0 + bj * HALF;
;                     const u32x4 gv = *(const u32x4*)(G + (size_t)row * ZW + col);
;                     u32x4 pv = (u32x4){0u, 0u, 0u, 0u};
;                     if (accum) pv = *(const u32x4*)(MB + (size_t)row * DM + col);
;                     const f32x4 a0 = acc[ai][bj][m][0], a1 = acc[ai][bj][m][1];
;                     u32x4 o;
;                     o.x = pk2(bflo(pv.x) + bflo(gv.x) * a0[0], bfhi(pv.x) + bfhi(gv.x) * a0[1]);
;                     o.y = pk2(bflo(pv.y) + bflo(gv.y) * a0[2], bfhi(pv.y) + bfhi(gv.y) * a0[3]);
;                     o.z = pk2(bflo(pv.z) + bflo(gv.z) * a1[0], bfhi(pv.z) + bfhi(gv.z) * a1[1]);
;                     o.w = pk2(bflo(pv.w) + bflo(gv.w) * a1[2], bfhi(pv.w) + bfhi(gv.w) * a1[3]);
;                     *(u32x4*)(MB + (size_t)row * DM + col) = o;
	v_lshlrev_b32_e32 v128, 16, v226
	v_and_b32_e32 v129, 0xffff0000, v226
	v_lshlrev_b32_e32 v130, 16, v230
	v_and_b32_e32 v131, 0xffff0000, v230
	v_pk_fma_f32 v[44:45], v[44:45], v[128:129], v[130:131]
	v_lshlrev_b32_e32 v128, 16, v227
	v_and_b32_e32 v129, 0xffff0000, v227
	v_lshlrev_b32_e32 v130, 16, v231
	v_and_b32_e32 v131, 0xffff0000, v231
	v_pk_fma_f32 v[46:47], v[46:47], v[128:129], v[130:131]
	v_lshlrev_b32_e32 v128, 16, v228
	v_and_b32_e32 v129, 0xffff0000, v228
	v_lshlrev_b32_e32 v130, 16, v232
	v_and_b32_e32 v131, 0xffff0000, v232
	v_pk_fma_f32 v[40:41], v[40:41], v[128:129], v[130:131]
	v_lshlrev_b32_e32 v128, 16, v229
	v_and_b32_e32 v129, 0xffff0000, v229
	v_lshlrev_b32_e32 v130, 16, v233
	v_and_b32_e32 v131, 0xffff0000, v233
	v_pk_fma_f32 v[42:43], v[42:43], v[128:129], v[130:131]
	v_cvt_pk_bf16_f32 v44, v44, v45
	v_cvt_pk_bf16_f32 v45, v46, v47
	v_cvt_pk_bf16_f32 v46, v40, v41
	v_cvt_pk_bf16_f32 v47, v42, v43
	s_mov_b32 s100, 0x90000
	v_lshl_add_u64 v[164:165], v[168:169], 0, s[100:101]
	global_store_dwordx4 v[164:165], v[44:47], off
	s_waitcnt vmcnt(13)
	v_lshlrev_b32_e32 v128, 16, v184
	v_and_b32_e32 v129, 0xffff0000, v184
	v_lshlrev_b32_e32 v130, 16, v188
	v_and_b32_e32 v131, 0xffff0000, v188
	v_pk_fma_f32 v[36:37], v[36:37], v[128:129], v[130:131]
	v_lshlrev_b32_e32 v128, 16, v185
	v_and_b32_e32 v129, 0xffff0000, v185
	v_lshlrev_b32_e32 v130, 16, v189
	v_and_b32_e32 v131, 0xffff0000, v189
	v_pk_fma_f32 v[38:39], v[38:39], v[128:129], v[130:131]
	v_lshlrev_b32_e32 v128, 16, v186
	v_and_b32_e32 v129, 0xffff0000, v186
	v_lshlrev_b32_e32 v130, 16, v190
	v_and_b32_e32 v131, 0xffff0000, v190
	v_pk_fma_f32 v[32:33], v[32:33], v[128:129], v[130:131]
	v_lshlrev_b32_e32 v128, 16, v187
	v_and_b32_e32 v129, 0xffff0000, v187
	v_lshlrev_b32_e32 v130, 16, v191
	v_and_b32_e32 v131, 0xffff0000, v191
	v_pk_fma_f32 v[34:35], v[34:35], v[128:129], v[130:131]
	v_cvt_pk_bf16_f32 v36, v36, v37
	v_cvt_pk_bf16_f32 v37, v38, v39
	v_cvt_pk_bf16_f32 v38, v32, v33
	v_cvt_pk_bf16_f32 v39, v34, v35
	s_mov_b32 s100, 0x90000
	v_lshl_add_u64 v[164:165], v[168:169], 0, s[100:101]
	global_store_dwordx4 v[164:165], v[36:39], off offset:256
	s_waitcnt vmcnt(11)
	v_lshlrev_b32_e32 v128, 16, v194
	v_and_b32_e32 v129, 0xffff0000, v194
	v_lshlrev_b32_e32 v130, 16, v198
	v_and_b32_e32 v131, 0xffff0000, v198
	v_pk_fma_f32 v[28:29], v[28:29], v[128:129], v[130:131]
	v_lshlrev_b32_e32 v128, 16, v195
	v_and_b32_e32 v129, 0xffff0000, v195
	v_lshlrev_b32_e32 v130, 16, v199
	v_and_b32_e32 v131, 0xffff0000, v199
	v_pk_fma_f32 v[30:31], v[30:31], v[128:129], v[130:131]
	v_lshlrev_b32_e32 v128, 16, v196
	v_and_b32_e32 v129, 0xffff0000, v196
	v_lshlrev_b32_e32 v130, 16, v200
	v_and_b32_e32 v131, 0xffff0000, v200
	v_pk_fma_f32 v[24:25], v[24:25], v[128:129], v[130:131]
	v_lshlrev_b32_e32 v128, 16, v197
	v_and_b32_e32 v129, 0xffff0000, v197
	v_lshlrev_b32_e32 v130, 16, v201
	v_and_b32_e32 v131, 0xffff0000, v201
	v_pk_fma_f32 v[26:27], v[26:27], v[128:129], v[130:131]
	v_cvt_pk_bf16_f32 v28, v28, v29
	v_cvt_pk_bf16_f32 v29, v30, v31
	v_cvt_pk_bf16_f32 v30, v24, v25
	v_cvt_pk_bf16_f32 v31, v26, v27
	s_mov_b32 s100, 0xa0000
	v_lshl_add_u64 v[164:165], v[168:169], 0, s[100:101]
	global_store_dwordx4 v[164:165], v[28:31], off
	s_waitcnt vmcnt(9)
	v_lshlrev_b32_e32 v128, 16, v202
	v_and_b32_e32 v129, 0xffff0000, v202
	v_lshlrev_b32_e32 v130, 16, v206
	v_and_b32_e32 v131, 0xffff0000, v206
	v_pk_fma_f32 v[20:21], v[20:21], v[128:129], v[130:131]
	v_lshlrev_b32_e32 v128, 16, v203
	v_and_b32_e32 v129, 0xffff0000, v203
	v_lshlrev_b32_e32 v130, 16, v207
	v_and_b32_e32 v131, 0xffff0000, v207
	v_pk_fma_f32 v[22:23], v[22:23], v[128:129], v[130:131]
	v_lshlrev_b32_e32 v128, 16, v204
	v_and_b32_e32 v129, 0xffff0000, v204
	v_lshlrev_b32_e32 v130, 16, v208
	v_and_b32_e32 v131, 0xffff0000, v208
	v_pk_fma_f32 v[16:17], v[16:17], v[128:129], v[130:131]
	v_lshlrev_b32_e32 v128, 16, v205
	v_and_b32_e32 v129, 0xffff0000, v205
	v_lshlrev_b32_e32 v130, 16, v209
	v_and_b32_e32 v131, 0xffff0000, v209
	v_pk_fma_f32 v[18:19], v[18:19], v[128:129], v[130:131]
	v_cvt_pk_bf16_f32 v20, v20, v21
	v_cvt_pk_bf16_f32 v21, v22, v23
	v_cvt_pk_bf16_f32 v22, v16, v17
	v_cvt_pk_bf16_f32 v23, v18, v19
	s_mov_b32 s100, 0xa0000
	v_lshl_add_u64 v[164:165], v[168:169], 0, s[100:101]
	global_store_dwordx4 v[164:165], v[20:23], off offset:256
	s_waitcnt vmcnt(7)
	v_lshlrev_b32_e32 v128, 16, v210
	v_and_b32_e32 v129, 0xffff0000, v210
	v_lshlrev_b32_e32 v130, 16, v214
	v_and_b32_e32 v131, 0xffff0000, v214
	v_pk_fma_f32 v[12:13], v[12:13], v[128:129], v[130:131]
	v_lshlrev_b32_e32 v128, 16, v211
	v_and_b32_e32 v129, 0xffff0000, v211
	v_lshlrev_b32_e32 v130, 16, v215
	v_and_b32_e32 v131, 0xffff0000, v215
	v_pk_fma_f32 v[14:15], v[14:15], v[128:129], v[130:131]
	v_lshlrev_b32_e32 v128, 16, v212
	v_and_b32_e32 v129, 0xffff0000, v212
	v_lshlrev_b32_e32 v130, 16, v216
	v_and_b32_e32 v131, 0xffff0000, v216
	v_pk_fma_f32 v[8:9], v[8:9], v[128:129], v[130:131]
	v_lshlrev_b32_e32 v128, 16, v213
	v_and_b32_e32 v129, 0xffff0000, v213
	v_lshlrev_b32_e32 v130, 16, v217
	v_and_b32_e32 v131, 0xffff0000, v217
	v_pk_fma_f32 v[10:11], v[10:11], v[128:129], v[130:131]
	v_cvt_pk_bf16_f32 v12, v12, v13
	v_cvt_pk_bf16_f32 v13, v14, v15
	v_cvt_pk_bf16_f32 v14, v8, v9
	v_cvt_pk_bf16_f32 v15, v10, v11
	s_mov_b32 s100, 0xb0000
	v_lshl_add_u64 v[164:165], v[168:169], 0, s[100:101]
	global_store_dwordx4 v[164:165], v[12:15], off
	s_waitcnt vmcnt(5)
	v_lshlrev_b32_e32 v128, 16, v218
	v_and_b32_e32 v129, 0xffff0000, v218
	v_lshlrev_b32_e32 v130, 16, v222
	v_and_b32_e32 v131, 0xffff0000, v222
	v_pk_fma_f32 v[4:5], v[4:5], v[128:129], v[130:131]
	v_lshlrev_b32_e32 v128, 16, v219
	v_and_b32_e32 v129, 0xffff0000, v219
	v_lshlrev_b32_e32 v130, 16, v223
	v_and_b32_e32 v131, 0xffff0000, v223
	v_pk_fma_f32 v[6:7], v[6:7], v[128:129], v[130:131]
	v_lshlrev_b32_e32 v128, 16, v220
	v_and_b32_e32 v129, 0xffff0000, v220
	v_lshlrev_b32_e32 v130, 16, v224
	v_and_b32_e32 v131, 0xffff0000, v224
	v_pk_fma_f32 v[0:1], v[0:1], v[128:129], v[130:131]
	v_lshlrev_b32_e32 v128, 16, v221
	v_and_b32_e32 v129, 0xffff0000, v221
	v_lshlrev_b32_e32 v130, 16, v225
	v_and_b32_e32 v131, 0xffff0000, v225
	v_pk_fma_f32 v[2:3], v[2:3], v[128:129], v[130:131]
	v_cvt_pk_bf16_f32 v4, v4, v5
	v_cvt_pk_bf16_f32 v5, v6, v7
	v_cvt_pk_bf16_f32 v6, v0, v1
	v_cvt_pk_bf16_f32 v7, v2, v3
	s_mov_b32 s100, 0xb0000
	v_lshl_add_u64 v[164:165], v[168:169], 0, s[100:101]
	global_store_dwordx4 v[164:165], v[4:7], off offset:256
	s_branch .Lbrn_done
; __device__ __forceinline__ unsigned pk2(float lo, float hi) { const f32v2_t v = {lo, hi}; const bf16v2_t b = __builtin_convertvector(v, bf16v2_t); return __builtin_bit_cast(unsigned, b); }
; __device__ __forceinline__ float bflo(unsigned w) { return __uint_as_float(w << 16); }
; __device__ __forceinline__ float bfhi(unsigned w) { return __uint_as_float(w & 0xffff0000u); }
;     __device__ __forceinline__ void operator()(AccRef acc, const Unit& u, int wr, int wc, int fr, int fq) const {
;     ...
;                     const u32x4 gv = *(const u32x4*)(G + (size_t)row * ZW + col);
;                     u32x4 pv = (u32x4){0u, 0u, 0u, 0u};
;                     if (accum) pv = *(const u32x4*)(MB + (size_t)row * DM + col);
;                     const f32x4 a0 = acc[ai][bj][m][0], a1 = acc[ai][bj][m][1];
;                     u32x4 o;
;                     o.x = pk2(bflo(pv.x) + bflo(gv.x) * a0[0], bfhi(pv.x) + bfhi(gv.x) * a0[1]);
;                     o.y = pk2(bflo(pv.y) + bflo(gv.y) * a0[2], bfhi(pv.y) + bfhi(gv.y) * a0[3]);
;                     o.z = pk2(bflo(pv.z) + bflo(gv.z) * a1[0], bfhi(pv.z) + bfhi(gv.z) * a1[1]);
;                     o.w = pk2(bflo(pv.w) + bflo(gv.w) * a1[2], bfhi(pv.w) + bfhi(gv.w) * a1[3]);
;                     *(u32x4*)(MB + (size_t)row * DM + col) = o;
.Lbrn_noacc:
	v_mov_b32_e32 v130, 0
	v_mov_b32_e32 v131, 0
	s_mov_b32 s100, 0x0
	v_lshl_add_u64 v[132:133], v[170:171], 0, s[100:101]
	global_load_dwordx4 v[194:197], v[132:133], off
	s_mov_b32 s100, 0x0
	v_lshl_add_u64 v[132:133], v[170:171], 0, s[100:101]
	global_load_dwordx4 v[202:205], v[132:133], off offset:256
	s_mov_b32 s100, 0x50000
	v_lshl_add_u64 v[132:133], v[170:171], 0, s[100:101]
	global_load_dwordx4 v[210:213], v[132:133], off
	s_mov_b32 s100, 0x50000
	v_lshl_add_u64 v[132:133], v[170:171], 0, s[100:101]
	global_load_dwordx4 v[218:221], v[132:133], off offset:256
	s_mov_b32 s100, 0xa0000
	v_lshl_add_u64 v[132:133], v[170:171], 0, s[100:101]
	global_load_dwordx4 v[226:229], v[132:133], off
	s_mov_b32 s100, 0xa0000
	v_lshl_add_u64 v[132:133], v[170:171], 0, s[100:101]
	global_load_dwordx4 v[184:187], v[132:133], off offset:256
	s_waitcnt vmcnt(5)
	v_lshlrev_b32_e32 v128, 16, v194
	v_and_b32_e32 v129, 0xffff0000, v194
	v_pk_fma_f32 v[124:125], v[124:125], v[128:129], v[130:131]
	v_lshlrev_b32_e32 v128, 16, v195
	v_and_b32_e32 v129, 0xffff0000, v195
	v_pk_fma_f32 v[126:127], v[126:127], v[128:129], v[130:131]
	v_lshlrev_b32_e32 v128, 16, v196
	v_and_b32_e32 v129, 0xffff0000, v196
	v_pk_fma_f32 v[120:121], v[120:121], v[128:129], v[130:131]
	v_lshlrev_b32_e32 v128, 16, v197
	v_and_b32_e32 v129, 0xffff0000, v197
	v_pk_fma_f32 v[122:123], v[122:123], v[128:129], v[130:131]
	v_cvt_pk_bf16_f32 v124, v124, v125
	v_cvt_pk_bf16_f32 v125, v126, v127
	v_cvt_pk_bf16_f32 v126, v120, v121
	v_cvt_pk_bf16_f32 v127, v122, v123
	s_mov_b32 s100, 0x0
	v_lshl_add_u64 v[164:165], v[168:169], 0, s[100:101]
	global_store_dwordx4 v[164:165], v[124:127], off
	s_mov_b32 s100, 0xf0000
	v_lshl_add_u64 v[132:133], v[170:171], 0, s[100:101]
	global_load_dwordx4 v[194:197], v[132:133], off
	s_waitcnt vmcnt(6)
	v_lshlrev_b32_e32 v128, 16, v202
	v_and_b32_e32 v129, 0xffff0000, v202
	v_pk_fma_f32 v[116:117], v[116:117], v[128:129], v[130:131]
	v_lshlrev_b32_e32 v128, 16, v203
	v_and_b32_e32 v129, 0xffff0000, v203
	v_pk_fma_f32 v[118:119], v[118:119], v[128:129], v[130:131]
	v_lshlrev_b32_e32 v128, 16, v204
	v_and_b32_e32 v129, 0xffff0000, v204
	v_pk_fma_f32 v[112:113], v[112:113], v[128:129], v[130:131]
	v_lshlrev_b32_e32 v128, 16, v205
	v_and_b32_e32 v129, 0xffff0000, v205
	v_pk_fma_f32 v[114:115], v[114:115], v[128:129], v[130:131]
	v_cvt_pk_bf16_f32 v116, v116, v117
	v_cvt_pk_bf16_f32 v117, v118, v119
	v_cvt_pk_bf16_f32 v118, v112, v113
	v_cvt_pk_bf16_f32 v119, v114, v115
	s_mov_b32 s100, 0x0
	v_lshl_add_u64 v[164:165], v[168:169], 0, s[100:101]
	global_store_dwordx4 v[164:165], v[116:119], off offset:256
	s_mov_b32 s100, 0xf0000
	v_lshl_add_u64 v[132:133], v[170:171], 0, s[100:101]
	global_load_dwordx4 v[202:205], v[132:133], off offset:256
	s_waitcnt vmcnt(7)
	v_lshlrev_b32_e32 v128, 16, v210
	v_and_b32_e32 v129, 0xffff0000, v210
	v_pk_fma_f32 v[108:109], v[108:109], v[128:129], v[130:131]
	v_lshlrev_b32_e32 v128, 16, v211
	v_and_b32_e32 v129, 0xffff0000, v211
	v_pk_fma_f32 v[110:111], v[110:111], v[128:129], v[130:131]
	v_lshlrev_b32_e32 v128, 16, v212
	v_and_b32_e32 v129, 0xffff0000, v212
	v_pk_fma_f32 v[104:105], v[104:105], v[128:129], v[130:131]
	v_lshlrev_b32_e32 v128, 16, v213
	v_and_b32_e32 v129, 0xffff0000, v213
	v_pk_fma_f32 v[106:107], v[106:107], v[128:129], v[130:131]
	v_cvt_pk_bf16_f32 v108, v108, v109
	v_cvt_pk_bf16_f32 v109, v110, v111
	v_cvt_pk_bf16_f32 v110, v104, v105
	v_cvt_pk_bf16_f32 v111, v106, v107
	s_mov_b32 s100, 0x10000
	v_lshl_add_u64 v[164:165], v[168:169], 0, s[100:101]
	global_store_dwordx4 v[164:165], v[108:111], off
	s_mov_b32 s100, 0x280000
	v_lshl_add_u64 v[132:133], v[170:171], 0, s[100:101]
	global_load_dwordx4 v[210:213], v[132:133], off
	s_waitcnt vmcnt(8)
	v_lshlrev_b32_e32 v128, 16, v218
	v_and_b32_e32 v129, 0xffff0000, v218
	v_pk_fma_f32 v[100:101], v[100:101], v[128:129], v[130:131]
	v_lshlrev_b32_e32 v128, 16, v219
	v_and_b32_e32 v129, 0xffff0000, v219
	v_pk_fma_f32 v[102:103], v[102:103], v[128:129], v[130:131]
	v_lshlrev_b32_e32 v128, 16, v220
	v_and_b32_e32 v129, 0xffff0000, v220
	v_pk_fma_f32 v[96:97], v[96:97], v[128:129], v[130:131]
	v_lshlrev_b32_e32 v128, 16, v221
	v_and_b32_e32 v129, 0xffff0000, v221
	v_pk_fma_f32 v[98:99], v[98:99], v[128:129], v[130:131]
	v_cvt_pk_bf16_f32 v100, v100, v101
	v_cvt_pk_bf16_f32 v101, v102, v103
	v_cvt_pk_bf16_f32 v102, v96, v97
	v_cvt_pk_bf16_f32 v103, v98, v99
	s_mov_b32 s100, 0x10000
	v_lshl_add_u64 v[164:165], v[168:169], 0, s[100:101]
	global_store_dwordx4 v[164:165], v[100:103], off offset:256
	s_mov_b32 s100, 0x280000
	v_lshl_add_u64 v[132:133], v[170:171], 0, s[100:101]
	global_load_dwordx4 v[218:221], v[132:133], off offset:256
	s_waitcnt vmcnt(9)
	v_lshlrev_b32_e32 v128, 16, v226
	v_and_b32_e32 v129, 0xffff0000, v226
	v_pk_fma_f32 v[92:93], v[92:93], v[128:129], v[130:131]
	v_lshlrev_b32_e32 v128, 16, v227
	v_and_b32_e32 v129, 0xffff0000, v227
	v_pk_fma_f32 v[94:95], v[94:95], v[128:129], v[130:131]
	v_lshlrev_b32_e32 v128, 16, v228
	v_and_b32_e32 v129, 0xffff0000, v228
	v_pk_fma_f32 v[88:89], v[88:89], v[128:129], v[130:131]
	v_lshlrev_b32_e32 v128, 16, v229
	v_and_b32_e32 v129, 0xffff0000, v229
	v_pk_fma_f32 v[90:91], v[90:91], v[128:129], v[130:131]
	v_cvt_pk_bf16_f32 v92, v92, v93
	v_cvt_pk_bf16_f32 v93, v94, v95
	v_cvt_pk_bf16_f32 v94, v88, v89
	v_cvt_pk_bf16_f32 v95, v90, v91
	s_mov_b32 s100, 0x20000
	v_lshl_add_u64 v[164:165], v[168:169], 0, s[100:101]
	global_store_dwordx4 v[164:165], v[92:95], off
	s_mov_b32 s100, 0x2d0000
	v_lshl_add_u64 v[132:133], v[170:171], 0, s[100:101]
	global_load_dwordx4 v[226:229], v[132:133], off
	s_waitcnt vmcnt(10)
; __device__ __forceinline__ unsigned pk2(float lo, float hi) { const f32v2_t v = {lo, hi}; const bf16v2_t b = __builtin_convertvector(v, bf16v2_t); return __builtin_bit_cast(unsigned, b); }
; __device__ __forceinline__ float bflo(unsigned w) { return __uint_as_float(w << 16); }
; __device__ __forceinline__ float bfhi(unsigned w) { return __uint_as_float(w & 0xffff0000u); }
;     __device__ __forceinline__ void operator()(AccRef acc, const Unit& u, int wr, int wc, int fr, int fq) const {
;     ...
; #pragma unroll
;                 for (int bj = 0; bj < 2; ++bj) {
;                     const int col = col0 + bj * HALF;
;                     const u32x4 gv = *(const u32x4*)(G + (size_t)row * ZW + col);
;                     u32x4 pv = (u32x4){0u, 0u, 0u, 0u};
;                     if (accum) pv = *(const u32x4*)(MB + (size_t)row * DM + col);
;                     const f32x4 a0 = acc[ai][bj][m][0], a1 = acc[ai][bj][m][1];
;                     u32x4 o;
;                     o.x = pk2(bflo(pv.x) + bflo(gv.x) * a0[0], bfhi(pv.x) + bfhi(gv.x) * a0[1]);
;                     o.y = pk2(bflo(pv.y) + bflo(gv.y) * a0[2], bfhi(pv.y) + bfhi(gv.y) * a0[3]);
;                     o.z = pk2(bflo(pv.z) + bflo(gv.z) * a1[0], bfhi(pv.z) + bfhi(gv.z) * a1[1]);
;                     o.w = pk2(bflo(pv.w) + bflo(gv.w) * a1[2], bfhi(pv.w) + bfhi(gv.w) * a1[3]);
;                     *(u32x4*)(MB + (size_t)row * DM + col) = o;
	v_lshlrev_b32_e32 v128, 16, v184
	v_and_b32_e32 v129, 0xffff0000, v184
	v_pk_fma_f32 v[84:85], v[84:85], v[128:129], v[130:131]
	v_lshlrev_b32_e32 v128, 16, v185
	v_and_b32_e32 v129, 0xffff0000, v185
	v_pk_fma_f32 v[86:87], v[86:87], v[128:129], v[130:131]
	v_lshlrev_b32_e32 v128, 16, v186
	v_and_b32_e32 v129, 0xffff0000, v186
	v_pk_fma_f32 v[80:81], v[80:81], v[128:129], v[130:131]
	v_lshlrev_b32_e32 v128, 16, v187
	v_and_b32_e32 v129, 0xffff0000, v187
	v_pk_fma_f32 v[82:83], v[82:83], v[128:129], v[130:131]
	v_cvt_pk_bf16_f32 v84, v84, v85
	v_cvt_pk_bf16_f32 v85, v86, v87
	v_cvt_pk_bf16_f32 v86, v80, v81
	v_cvt_pk_bf16_f32 v87, v82, v83
	s_mov_b32 s100, 0x20000
	v_lshl_add_u64 v[164:165], v[168:169], 0, s[100:101]
	global_store_dwordx4 v[164:165], v[84:87], off offset:256
	s_mov_b32 s100, 0x2d0000
	v_lshl_add_u64 v[132:133], v[170:171], 0, s[100:101]
	global_load_dwordx4 v[184:187], v[132:133], off offset:256
	s_waitcnt vmcnt(10)
	v_lshlrev_b32_e32 v128, 16, v194
	v_and_b32_e32 v129, 0xffff0000, v194
	v_pk_fma_f32 v[76:77], v[76:77], v[128:129], v[130:131]
	v_lshlrev_b32_e32 v128, 16, v195
	v_and_b32_e32 v129, 0xffff0000, v195
	v_pk_fma_f32 v[78:79], v[78:79], v[128:129], v[130:131]
	v_lshlrev_b32_e32 v128, 16, v196
	v_and_b32_e32 v129, 0xffff0000, v196
	v_pk_fma_f32 v[72:73], v[72:73], v[128:129], v[130:131]
	v_lshlrev_b32_e32 v128, 16, v197
	v_and_b32_e32 v129, 0xffff0000, v197
	v_pk_fma_f32 v[74:75], v[74:75], v[128:129], v[130:131]
	v_cvt_pk_bf16_f32 v76, v76, v77
	v_cvt_pk_bf16_f32 v77, v78, v79
	v_cvt_pk_bf16_f32 v78, v72, v73
	v_cvt_pk_bf16_f32 v79, v74, v75
	s_mov_b32 s100, 0x30000
	v_lshl_add_u64 v[164:165], v[168:169], 0, s[100:101]
	global_store_dwordx4 v[164:165], v[76:79], off
	s_mov_b32 s100, 0x320000
	v_lshl_add_u64 v[132:133], v[170:171], 0, s[100:101]
	global_load_dwordx4 v[194:197], v[132:133], off
	s_waitcnt vmcnt(10)
	v_lshlrev_b32_e32 v128, 16, v202
	v_and_b32_e32 v129, 0xffff0000, v202
	v_pk_fma_f32 v[68:69], v[68:69], v[128:129], v[130:131]
	v_lshlrev_b32_e32 v128, 16, v203
	v_and_b32_e32 v129, 0xffff0000, v203
	v_pk_fma_f32 v[70:71], v[70:71], v[128:129], v[130:131]
	v_lshlrev_b32_e32 v128, 16, v204
	v_and_b32_e32 v129, 0xffff0000, v204
	v_pk_fma_f32 v[64:65], v[64:65], v[128:129], v[130:131]
	v_lshlrev_b32_e32 v128, 16, v205
	v_and_b32_e32 v129, 0xffff0000, v205
	v_pk_fma_f32 v[66:67], v[66:67], v[128:129], v[130:131]
	v_cvt_pk_bf16_f32 v68, v68, v69
	v_cvt_pk_bf16_f32 v69, v70, v71
	v_cvt_pk_bf16_f32 v70, v64, v65
	v_cvt_pk_bf16_f32 v71, v66, v67
	s_mov_b32 s100, 0x30000
	v_lshl_add_u64 v[164:165], v[168:169], 0, s[100:101]
	global_store_dwordx4 v[164:165], v[68:71], off offset:256
	s_mov_b32 s100, 0x320000
	v_lshl_add_u64 v[132:133], v[170:171], 0, s[100:101]
	global_load_dwordx4 v[202:205], v[132:133], off offset:256
	s_waitcnt vmcnt(10)
	v_lshlrev_b32_e32 v128, 16, v210
	v_and_b32_e32 v129, 0xffff0000, v210
	v_pk_fma_f32 v[60:61], v[60:61], v[128:129], v[130:131]
	v_lshlrev_b32_e32 v128, 16, v211
	v_and_b32_e32 v129, 0xffff0000, v211
	v_pk_fma_f32 v[62:63], v[62:63], v[128:129], v[130:131]
	v_lshlrev_b32_e32 v128, 16, v212
	v_and_b32_e32 v129, 0xffff0000, v212
	v_pk_fma_f32 v[56:57], v[56:57], v[128:129], v[130:131]
	v_lshlrev_b32_e32 v128, 16, v213
	v_and_b32_e32 v129, 0xffff0000, v213
	v_pk_fma_f32 v[58:59], v[58:59], v[128:129], v[130:131]
	v_cvt_pk_bf16_f32 v60, v60, v61
	v_cvt_pk_bf16_f32 v61, v62, v63
	v_cvt_pk_bf16_f32 v62, v56, v57
	v_cvt_pk_bf16_f32 v63, v58, v59
	s_mov_b32 s100, 0x80000
	v_lshl_add_u64 v[164:165], v[168:169], 0, s[100:101]
	global_store_dwordx4 v[164:165], v[60:63], off
	s_mov_b32 s100, 0x370000
	v_lshl_add_u64 v[132:133], v[170:171], 0, s[100:101]
	global_load_dwordx4 v[210:213], v[132:133], off
	s_waitcnt vmcnt(10)
	v_lshlrev_b32_e32 v128, 16, v218
	v_and_b32_e32 v129, 0xffff0000, v218
	v_pk_fma_f32 v[52:53], v[52:53], v[128:129], v[130:131]
	v_lshlrev_b32_e32 v128, 16, v219
	v_and_b32_e32 v129, 0xffff0000, v219
	v_pk_fma_f32 v[54:55], v[54:55], v[128:129], v[130:131]
	v_lshlrev_b32_e32 v128, 16, v220
	v_and_b32_e32 v129, 0xffff0000, v220
	v_pk_fma_f32 v[48:49], v[48:49], v[128:129], v[130:131]
	v_lshlrev_b32_e32 v128, 16, v221
	v_and_b32_e32 v129, 0xffff0000, v221
	v_pk_fma_f32 v[50:51], v[50:51], v[128:129], v[130:131]
	v_cvt_pk_bf16_f32 v52, v52, v53
	v_cvt_pk_bf16_f32 v53, v54, v55
	v_cvt_pk_bf16_f32 v54, v48, v49
	v_cvt_pk_bf16_f32 v55, v50, v51
	s_mov_b32 s100, 0x80000
	v_lshl_add_u64 v[164:165], v[168:169], 0, s[100:101]
	global_store_dwordx4 v[164:165], v[52:55], off offset:256
	s_mov_b32 s100, 0x370000
	v_lshl_add_u64 v[132:133], v[170:171], 0, s[100:101]
	global_load_dwordx4 v[218:221], v[132:133], off offset:256
	s_waitcnt vmcnt(10)
; __device__ __forceinline__ unsigned pk2(float lo, float hi) { const f32v2_t v = {lo, hi}; const bf16v2_t b = __builtin_convertvector(v, bf16v2_t); return __builtin_bit_cast(unsigned, b); }
; __device__ __forceinline__ float bflo(unsigned w) { return __uint_as_float(w << 16); }
; __device__ __forceinline__ float bfhi(unsigned w) { return __uint_as_float(w & 0xffff0000u); }
; #define PG8_BAR __builtin_amdgcn_s_barrier()
; template <class Epi, class Sched>
; __device__ __forceinline__ void gemm_phase(LAS unsigned char* lds, const Gemm g, const Sched& S, const Epi& E) {
;     ...
;         if (!has_next) break;
; #pragma unroll
;         for (int a = 0; a < 2; ++a)
; #pragma unroll
;             for (int b = 0; b < 2; ++b)
; #pragma unroll
;                 for (int m = 0; m < 4; ++m)
; #pragma unroll
;                     for (int n = 0; n < 2; ++n) acc[a][b][m][n] = (f32x4){0.f, 0.f, 0.f, 0.f};
;         cur = nxt; cA = nA; cB = nB; ++ui;
;         if (Sched::SEGMENTED) nt = S.nt(cur);
;     ...
;         if (wr == 1) PG8_BAR;
;     __device__ __forceinline__ void operator()(AccRef acc, const Unit& u, int wr, int wc, int fr, int fq) const {
;     ...
; #pragma unroll
;                 for (int bj = 0; bj < 2; ++bj) {
;                     const int col = col0 + bj * HALF;
;                     const u32x4 gv = *(const u32x4*)(G + (size_t)row * ZW + col);
;                     u32x4 pv = (u32x4){0u, 0u, 0u, 0u};
;                     if (accum) pv = *(const u32x4*)(MB + (size_t)row * DM + col);
;                     const f32x4 a0 = acc[ai][bj][m][0], a1 = acc[ai][bj][m][1];
;                     u32x4 o;
;                     o.x = pk2(bflo(pv.x) + bflo(gv.x) * a0[0], bfhi(pv.x) + bfhi(gv.x) * a0[1]);
;                     o.y = pk2(bflo(pv.y) + bflo(gv.y) * a0[2], bfhi(pv.y) + bfhi(gv.y) * a0[3]);
;                     o.z = pk2(bflo(pv.z) + bflo(gv.z) * a1[0], bfhi(pv.z) + bfhi(gv.z) * a1[1]);
;                     o.w = pk2(bflo(pv.w) + bflo(gv.w) * a1[2], bfhi(pv.w) + bfhi(gv.w) * a1[3]);
;                     *(u32x4*)(MB + (size_t)row * DM + col) = o;
	v_lshlrev_b32_e32 v128, 16, v226
	v_and_b32_e32 v129, 0xffff0000, v226
	v_pk_fma_f32 v[44:45], v[44:45], v[128:129], v[130:131]
	v_lshlrev_b32_e32 v128, 16, v227
	v_and_b32_e32 v129, 0xffff0000, v227
	v_pk_fma_f32 v[46:47], v[46:47], v[128:129], v[130:131]
	v_lshlrev_b32_e32 v128, 16, v228
	v_and_b32_e32 v129, 0xffff0000, v228
	v_pk_fma_f32 v[40:41], v[40:41], v[128:129], v[130:131]
	v_lshlrev_b32_e32 v128, 16, v229
	v_and_b32_e32 v129, 0xffff0000, v229
	v_pk_fma_f32 v[42:43], v[42:43], v[128:129], v[130:131]
	v_cvt_pk_bf16_f32 v44, v44, v45
	v_cvt_pk_bf16_f32 v45, v46, v47
	v_cvt_pk_bf16_f32 v46, v40, v41
	v_cvt_pk_bf16_f32 v47, v42, v43
	s_mov_b32 s100, 0x90000
	v_lshl_add_u64 v[164:165], v[168:169], 0, s[100:101]
	global_store_dwordx4 v[164:165], v[44:47], off
	s_waitcnt vmcnt(9)
	v_lshlrev_b32_e32 v128, 16, v184
	v_and_b32_e32 v129, 0xffff0000, v184
	v_pk_fma_f32 v[36:37], v[36:37], v[128:129], v[130:131]
	v_lshlrev_b32_e32 v128, 16, v185
	v_and_b32_e32 v129, 0xffff0000, v185
	v_pk_fma_f32 v[38:39], v[38:39], v[128:129], v[130:131]
	v_lshlrev_b32_e32 v128, 16, v186
	v_and_b32_e32 v129, 0xffff0000, v186
	v_pk_fma_f32 v[32:33], v[32:33], v[128:129], v[130:131]
	v_lshlrev_b32_e32 v128, 16, v187
	v_and_b32_e32 v129, 0xffff0000, v187
	v_pk_fma_f32 v[34:35], v[34:35], v[128:129], v[130:131]
	v_cvt_pk_bf16_f32 v36, v36, v37
	v_cvt_pk_bf16_f32 v37, v38, v39
	v_cvt_pk_bf16_f32 v38, v32, v33
	v_cvt_pk_bf16_f32 v39, v34, v35
	s_mov_b32 s100, 0x90000
	v_lshl_add_u64 v[164:165], v[168:169], 0, s[100:101]
	global_store_dwordx4 v[164:165], v[36:39], off offset:256
	s_waitcnt vmcnt(8)
	v_lshlrev_b32_e32 v128, 16, v194
	v_and_b32_e32 v129, 0xffff0000, v194
	v_pk_fma_f32 v[28:29], v[28:29], v[128:129], v[130:131]
	v_lshlrev_b32_e32 v128, 16, v195
	v_and_b32_e32 v129, 0xffff0000, v195
	v_pk_fma_f32 v[30:31], v[30:31], v[128:129], v[130:131]
	v_lshlrev_b32_e32 v128, 16, v196
	v_and_b32_e32 v129, 0xffff0000, v196
	v_pk_fma_f32 v[24:25], v[24:25], v[128:129], v[130:131]
	v_lshlrev_b32_e32 v128, 16, v197
	v_and_b32_e32 v129, 0xffff0000, v197
	v_pk_fma_f32 v[26:27], v[26:27], v[128:129], v[130:131]
	v_cvt_pk_bf16_f32 v28, v28, v29
	v_cvt_pk_bf16_f32 v29, v30, v31
	v_cvt_pk_bf16_f32 v30, v24, v25
	v_cvt_pk_bf16_f32 v31, v26, v27
	s_mov_b32 s100, 0xa0000
	v_lshl_add_u64 v[164:165], v[168:169], 0, s[100:101]
	global_store_dwordx4 v[164:165], v[28:31], off
	s_waitcnt vmcnt(7)
	v_lshlrev_b32_e32 v128, 16, v202
	v_and_b32_e32 v129, 0xffff0000, v202
	v_pk_fma_f32 v[20:21], v[20:21], v[128:129], v[130:131]
	v_lshlrev_b32_e32 v128, 16, v203
	v_and_b32_e32 v129, 0xffff0000, v203
	v_pk_fma_f32 v[22:23], v[22:23], v[128:129], v[130:131]
	v_lshlrev_b32_e32 v128, 16, v204
	v_and_b32_e32 v129, 0xffff0000, v204
	v_pk_fma_f32 v[16:17], v[16:17], v[128:129], v[130:131]
	v_lshlrev_b32_e32 v128, 16, v205
	v_and_b32_e32 v129, 0xffff0000, v205
	v_pk_fma_f32 v[18:19], v[18:19], v[128:129], v[130:131]
	v_cvt_pk_bf16_f32 v20, v20, v21
	v_cvt_pk_bf16_f32 v21, v22, v23
	v_cvt_pk_bf16_f32 v22, v16, v17
	v_cvt_pk_bf16_f32 v23, v18, v19
	s_mov_b32 s100, 0xa0000
	v_lshl_add_u64 v[164:165], v[168:169], 0, s[100:101]
	global_store_dwordx4 v[164:165], v[20:23], off offset:256
	s_waitcnt vmcnt(6)
	v_lshlrev_b32_e32 v128, 16, v210
	v_and_b32_e32 v129, 0xffff0000, v210
	v_pk_fma_f32 v[12:13], v[12:13], v[128:129], v[130:131]
	v_lshlrev_b32_e32 v128, 16, v211
	v_and_b32_e32 v129, 0xffff0000, v211
	v_pk_fma_f32 v[14:15], v[14:15], v[128:129], v[130:131]
	v_lshlrev_b32_e32 v128, 16, v212
	v_and_b32_e32 v129, 0xffff0000, v212
	v_pk_fma_f32 v[8:9], v[8:9], v[128:129], v[130:131]
	v_lshlrev_b32_e32 v128, 16, v213
	v_and_b32_e32 v129, 0xffff0000, v213
	v_pk_fma_f32 v[10:11], v[10:11], v[128:129], v[130:131]
	v_cvt_pk_bf16_f32 v12, v12, v13
	v_cvt_pk_bf16_f32 v13, v14, v15
	v_cvt_pk_bf16_f32 v14, v8, v9
	v_cvt_pk_bf16_f32 v15, v10, v11
	s_mov_b32 s100, 0xb0000
	v_lshl_add_u64 v[164:165], v[168:169], 0, s[100:101]
	global_store_dwordx4 v[164:165], v[12:15], off
	s_waitcnt vmcnt(5)
	v_lshlrev_b32_e32 v128, 16, v218
	v_and_b32_e32 v129, 0xffff0000, v218
	v_pk_fma_f32 v[4:5], v[4:5], v[128:129], v[130:131]
	v_lshlrev_b32_e32 v128, 16, v219
	v_and_b32_e32 v129, 0xffff0000, v219
	v_pk_fma_f32 v[6:7], v[6:7], v[128:129], v[130:131]
	v_lshlrev_b32_e32 v128, 16, v220
	v_and_b32_e32 v129, 0xffff0000, v220
	v_pk_fma_f32 v[0:1], v[0:1], v[128:129], v[130:131]
	v_lshlrev_b32_e32 v128, 16, v221
	v_and_b32_e32 v129, 0xffff0000, v221
	v_pk_fma_f32 v[2:3], v[2:3], v[128:129], v[130:131]
	v_cvt_pk_bf16_f32 v4, v4, v5
	v_cvt_pk_bf16_f32 v5, v6, v7
	v_cvt_pk_bf16_f32 v6, v0, v1
	v_cvt_pk_bf16_f32 v7, v2, v3
	s_mov_b32 s100, 0xb0000
	v_lshl_add_u64 v[164:165], v[168:169], 0, s[100:101]
	global_store_dwordx4 v[164:165], v[4:7], off offset:256
.Lbrn_done:
	s_and_b64 vcc, exec, s[38:39]
	s_mov_b64 s[22:23], -1
	s_cbranch_vccnz .LBB0_129
	s_cmp_eq_u32 s62, 1
	s_cselect_b32 s61, 16, 8
	s_andn2_b64 vcc, exec, s[42:43]
	s_cbranch_vccnz .LBB0_128
	s_barrier
	s_branch .LBB0_128

;     __device__ __forceinline__ void operator()(AccRef acc, const Unit& u, int wr, int wc, int fr, int fq) const {
;         const int row0 = u.pm * BM + wr * 64 + fr, col0 = u.pn * BM + wc * 32 + 8 * fq;
;         const bool sg = u.pn >= 16;
;         const bool ssm = (u.pn == 14) | (u.pn == 15);
;         const int cs = col0 - ZC_S;
;         bf16_t* const dst = ssm ? XS + (size_t)(cs >> 4) * T * 16 + (cs & 15) : Z + col0; const size_t pitch = ssm ? 16 : ZW; const size_t bjstep = ssm ? (size_t)8 * T * 16 : (size_t)HALF;
; #pragma unroll
;         for (int ai = 0; ai < 2; ++ai)
; #pragma unroll
;             for (int m = 0; m < 4; ++m) {
;                 const int row = row0 + ai * HALF + m * 16;
;                 const float rinv = rsqrtf((float)rss[row] * (1.f / (16777216.f * DM)) + EPS);
;                 const float nrl = rinv * -1.4426950408889634f;
.LBB0_390:
	v_lshl_add_u32 v162, s57, 8, v181
	v_ashrrev_i32_e32 v163, 31, v162
	v_lshl_add_u64 v[164:165], v[162:163], 3, s[42:43]
	global_load_dwordx2 v[166:167], v[164:165], off
	global_load_dwordx2 v[210:211], v[164:165], off offset:128
	global_load_dwordx2 v[212:213], v[164:165], off offset:256
	global_load_dwordx2 v[214:215], v[164:165], off offset:384
	global_load_dwordx2 v[216:217], v[164:165], off offset:1024
	global_load_dwordx2 v[218:219], v[164:165], off offset:1152
	global_load_dwordx2 v[220:221], v[164:165], off offset:1280
	global_load_dwordx2 v[222:223], v[164:165], off offset:1408
	s_cmp_lt_i32 s56, 16
	s_cselect_b64 s[56:57], -1, 0
	s_mov_b64 s[40:41], -1
	s_waitcnt vmcnt(0)
	v_ffbh_u32_e32 v136, v167
	v_min_u32_e32 v136, 32, v136
	v_lshlrev_b64 v[166:167], v136, v[166:167]
	v_min_u32_e32 v163, 1, v166
	v_or_b32_e32 v163, v167, v163
	v_cvt_f32_u32_e32 v163, v163
	v_sub_u32_e32 v136, 32, v136
	v_ldexp_f32 v136, v163, v136
	v_fmamk_f32 v136, v136, 0x2e000000, v176
	v_cmp_gt_f32_e32 vcc, s7, v136
	v_mul_f32_e32 v163, 0x4b800000, v136
	s_nop 0
	v_cndmask_b32_e32 v136, v136, v163, vcc
	v_rsq_f32_e32 v136, v136
	s_nop 0
	v_mul_f32_e32 v163, 0x45800000, v136
	v_cndmask_b32_e32 v166, v136, v163, vcc
	v_mov_b32_e32 v167, v166
	s_and_b64 vcc, exec, s[56:57]
	s_cbranch_vccz .LBB0_392
	v_pk_mul_f32 v[170:171], v[124:125], v[166:167]
	s_mov_b64 s[40:41], 0

; __device__ __forceinline__ unsigned pk2(float lo, float hi) { const f32v2_t v = {lo, hi}; const bf16v2_t b = __builtin_convertvector(v, bf16v2_t); return __builtin_bit_cast(unsigned, b); }
; #define ST_OUT(p, v) __builtin_nontemporal_store((v), (p))
;     __device__ __forceinline__ void operator()(AccRef acc, const Unit& u, int wr, int wc, int fr, int fq) const {
;     ...
;                 const int row = row0 + ai * HALF + m * 16;
;                 const float rinv = rsqrtf((float)rss[row] * (1.f / (16777216.f * DM)) + EPS);
;                 const float nrl = rinv * -1.4426950408889634f;
; #pragma unroll
;                 for (int bj = 0; bj < 2; ++bj) {
;                     unsigned ow[4];
; #pragma unroll
;                     for (int n = 0; n < 2; ++n)
; #pragma unroll
;                         for (int jp = 0; jp < 2; ++jp) {
;                             const f32v2_t av = {acc[ai][bj][m][n][2 * jp], acc[ai][bj][m][n][2 * jp + 1]};
;                             f32v2_t hv;
;                             if (sg) { const f32v2_t t = av * nrl; f32v2_t e; e.x = __builtin_amdgcn_exp2f(t.x); e.y = __builtin_amdgcn_exp2f(t.y); const f32v2_t d = e + 1.0f;
;                                 hv.x = __builtin_amdgcn_rcpf(d.x); hv.y = __builtin_amdgcn_rcpf(d.y); }
;                             else hv = av * rinv;
;                             ow[n * 2 + jp] = pk2(hv.x, hv.y);
;                         }
;                     u32x4 o; o.x = ow[0]; o.y = ow[1]; o.z = ow[2]; o.w = ow[3];
;                     ST_OUT((u32x4*)(dst + (size_t)row * pitch + bj * bjstep), o);
.LBB0_410:
	s_lshl_b32 s56, s0, 1
	s_mov_b32 s57, s89
	v_cvt_pk_bf16_f32 v114, v122, v123
	v_cvt_pk_bf16_f32 v115, v116, v117
	v_cvt_pk_bf16_f32 v116, v118, v119
	v_cvt_pk_bf16_f32 v117, v112, v113
	v_lshl_add_u64 v[112:113], v[120:121], 0, s[56:57]
	global_store_dwordx4 v[112:113], v[114:117], off nt
	v_mov_b32_e32 v112, v210
	v_mov_b32_e32 v113, v211
	s_and_b64 vcc, exec, s[40:41]
	v_ffbh_u32_e32 v114, v113
	v_min_u32_e32 v114, 32, v114
	v_lshlrev_b64 v[112:113], v114, v[112:113]
	v_min_u32_e32 v112, 1, v112
	v_or_b32_e32 v112, v113, v112
	v_cvt_f32_u32_e32 v112, v112
	v_sub_u32_e32 v113, 32, v114
	v_ldexp_f32 v112, v112, v113
	v_fmamk_f32 v112, v112, 0x2e000000, v176
	v_mul_f32_e32 v113, 0x4b800000, v112
	v_cmp_gt_f32_e64 s[0:1], s7, v112
	s_nop 1
	v_cndmask_b32_e64 v112, v112, v113, s[0:1]
	v_rsq_f32_e32 v112, v112
	s_nop 0
	v_mul_f32_e32 v113, 0x45800000, v112
	v_cndmask_b32_e64 v114, v112, v113, s[0:1]
	v_mov_b32_e32 v115, v114
	s_mov_b64 s[0:1], -1
	s_cbranch_vccz .LBB0_551
	v_mul_f32_e32 v112, 0xbfb8aa3b, v114
	s_andn2_b64 vcc, exec, s[0:1]
	v_mov_b32_e32 v113, v112
	s_cbranch_vccz .LBB0_552

; __device__ __forceinline__ unsigned pk2(float lo, float hi) { const f32v2_t v = {lo, hi}; const bf16v2_t b = __builtin_convertvector(v, bf16v2_t); return __builtin_bit_cast(unsigned, b); }
; #define ST_OUT(p, v) __builtin_nontemporal_store((v), (p))
;     __device__ __forceinline__ void operator()(AccRef acc, const Unit& u, int wr, int wc, int fr, int fq) const {
;     ...
;                 const int row = row0 + ai * HALF + m * 16;
;                 const float rinv = rsqrtf((float)rss[row] * (1.f / (16777216.f * DM)) + EPS);
;                 const float nrl = rinv * -1.4426950408889634f;
; #pragma unroll
;                 for (int bj = 0; bj < 2; ++bj) {
;                     unsigned ow[4];
; #pragma unroll
;                     for (int n = 0; n < 2; ++n)
; #pragma unroll
;                         for (int jp = 0; jp < 2; ++jp) {
;                             const f32v2_t av = {acc[ai][bj][m][n][2 * jp], acc[ai][bj][m][n][2 * jp + 1]};
;                             f32v2_t hv;
;                             if (sg) { const f32v2_t t = av * nrl; f32v2_t e; e.x = __builtin_amdgcn_exp2f(t.x); e.y = __builtin_amdgcn_exp2f(t.y); const f32v2_t d = e + 1.0f;
;                                 hv.x = __builtin_amdgcn_rcpf(d.x); hv.y = __builtin_amdgcn_rcpf(d.y); }
;                             else hv = av * rinv;
;                             ow[n * 2 + jp] = pk2(hv.x, hv.y);
;                         }
;                     u32x4 o; o.x = ow[0]; o.y = ow[1]; o.z = ow[2]; o.w = ow[3];
;                     ST_OUT((u32x4*)(dst + (size_t)row * pitch + bj * bjstep), o);
.LBB0_428:
	s_mov_b32 s57, s89
	v_cvt_pk_bf16_f32 v98, v106, v107
	v_cvt_pk_bf16_f32 v99, v100, v101
	v_cvt_pk_bf16_f32 v100, v102, v103
	v_cvt_pk_bf16_f32 v101, v96, v97
	v_lshl_add_u64 v[96:97], v[104:105], 0, s[56:57]
	global_store_dwordx4 v[96:97], v[98:101], off nt
	v_mov_b32_e32 v96, v212
	v_mov_b32_e32 v97, v213
	s_and_b64 vcc, exec, s[40:41]
	v_ffbh_u32_e32 v98, v97
	v_min_u32_e32 v98, 32, v98
	v_lshlrev_b64 v[96:97], v98, v[96:97]
	v_min_u32_e32 v96, 1, v96
	v_or_b32_e32 v96, v97, v96
	v_cvt_f32_u32_e32 v96, v96
	v_sub_u32_e32 v97, 32, v98
	v_ldexp_f32 v96, v96, v97
	v_fmamk_f32 v96, v96, 0x2e000000, v176
	v_mul_f32_e32 v97, 0x4b800000, v96
	v_cmp_gt_f32_e64 s[0:1], s7, v96
	s_nop 1
	v_cndmask_b32_e64 v96, v96, v97, s[0:1]
	v_rsq_f32_e32 v96, v96
	s_nop 0
	v_mul_f32_e32 v97, 0x45800000, v96
	v_cndmask_b32_e64 v98, v96, v97, s[0:1]
	v_mov_b32_e32 v99, v98
	s_mov_b64 s[0:1], -1
	s_cbranch_vccz .LBB0_565
	v_mul_f32_e32 v96, 0xbfb8aa3b, v98
	s_andn2_b64 vcc, exec, s[0:1]
	v_mov_b32_e32 v97, v96
	s_cbranch_vccz .LBB0_566

; __device__ __forceinline__ unsigned pk2(float lo, float hi) { const f32v2_t v = {lo, hi}; const bf16v2_t b = __builtin_convertvector(v, bf16v2_t); return __builtin_bit_cast(unsigned, b); }
; #define ST_OUT(p, v) __builtin_nontemporal_store((v), (p))
;     __device__ __forceinline__ void operator()(AccRef acc, const Unit& u, int wr, int wc, int fr, int fq) const {
;     ...
;                 const int row = row0 + ai * HALF + m * 16;
;                 const float rinv = rsqrtf((float)rss[row] * (1.f / (16777216.f * DM)) + EPS);
;                 const float nrl = rinv * -1.4426950408889634f;
; #pragma unroll
;                 for (int bj = 0; bj < 2; ++bj) {
;                     unsigned ow[4];
; #pragma unroll
;                     for (int n = 0; n < 2; ++n)
; #pragma unroll
;                         for (int jp = 0; jp < 2; ++jp) {
;                             const f32v2_t av = {acc[ai][bj][m][n][2 * jp], acc[ai][bj][m][n][2 * jp + 1]};
;                             f32v2_t hv;
;                             if (sg) { const f32v2_t t = av * nrl; f32v2_t e; e.x = __builtin_amdgcn_exp2f(t.x); e.y = __builtin_amdgcn_exp2f(t.y); const f32v2_t d = e + 1.0f;
;                                 hv.x = __builtin_amdgcn_rcpf(d.x); hv.y = __builtin_amdgcn_rcpf(d.y); }
;                             else hv = av * rinv;
;                             ow[n * 2 + jp] = pk2(hv.x, hv.y);
;                         }
;                     u32x4 o; o.x = ow[0]; o.y = ow[1]; o.z = ow[2]; o.w = ow[3];
;                     ST_OUT((u32x4*)(dst + (size_t)row * pitch + bj * bjstep), o);
.LBB0_446:
	s_mov_b32 s57, s89
	v_cvt_pk_bf16_f32 v82, v90, v91
	v_cvt_pk_bf16_f32 v83, v84, v85
	v_cvt_pk_bf16_f32 v84, v86, v87
	v_cvt_pk_bf16_f32 v85, v80, v81
	v_lshl_add_u64 v[80:81], v[88:89], 0, s[56:57]
	global_store_dwordx4 v[80:81], v[82:85], off nt
	v_mov_b32_e32 v80, v214
	v_mov_b32_e32 v81, v215
	s_and_b64 vcc, exec, s[40:41]
	v_ffbh_u32_e32 v82, v81
	v_min_u32_e32 v82, 32, v82
	v_lshlrev_b64 v[80:81], v82, v[80:81]
	v_min_u32_e32 v80, 1, v80
	v_or_b32_e32 v80, v81, v80
	v_cvt_f32_u32_e32 v80, v80
	v_sub_u32_e32 v81, 32, v82
	v_ldexp_f32 v80, v80, v81
	v_fmamk_f32 v80, v80, 0x2e000000, v176
	v_mul_f32_e32 v81, 0x4b800000, v80
	v_cmp_gt_f32_e64 s[0:1], s7, v80
	s_nop 1
	v_cndmask_b32_e64 v80, v80, v81, s[0:1]
	v_rsq_f32_e32 v80, v80
	s_nop 0
	v_mul_f32_e32 v81, 0x45800000, v80
	v_cndmask_b32_e64 v82, v80, v81, s[0:1]
	v_mov_b32_e32 v83, v82
	s_mov_b64 s[0:1], -1
	s_cbranch_vccz .LBB0_579
	v_mul_f32_e32 v80, 0xbfb8aa3b, v82
	s_andn2_b64 vcc, exec, s[0:1]
	v_mov_b32_e32 v81, v80
	s_cbranch_vccz .LBB0_580

; __device__ __forceinline__ unsigned pk2(float lo, float hi) { const f32v2_t v = {lo, hi}; const bf16v2_t b = __builtin_convertvector(v, bf16v2_t); return __builtin_bit_cast(unsigned, b); }
; #define ST_OUT(p, v) __builtin_nontemporal_store((v), (p))
;     __device__ __forceinline__ void operator()(AccRef acc, const Unit& u, int wr, int wc, int fr, int fq) const {
;     ...
;                 const int row = row0 + ai * HALF + m * 16;
;                 const float rinv = rsqrtf((float)rss[row] * (1.f / (16777216.f * DM)) + EPS);
;                 const float nrl = rinv * -1.4426950408889634f;
; #pragma unroll
;                 for (int bj = 0; bj < 2; ++bj) {
;                     unsigned ow[4];
; #pragma unroll
;                     for (int n = 0; n < 2; ++n)
; #pragma unroll
;                         for (int jp = 0; jp < 2; ++jp) {
;                             const f32v2_t av = {acc[ai][bj][m][n][2 * jp], acc[ai][bj][m][n][2 * jp + 1]};
;                             f32v2_t hv;
;                             if (sg) { const f32v2_t t = av * nrl; f32v2_t e; e.x = __builtin_amdgcn_exp2f(t.x); e.y = __builtin_amdgcn_exp2f(t.y); const f32v2_t d = e + 1.0f;
;                                 hv.x = __builtin_amdgcn_rcpf(d.x); hv.y = __builtin_amdgcn_rcpf(d.y); }
;                             else hv = av * rinv;
;                             ow[n * 2 + jp] = pk2(hv.x, hv.y);
;                         }
;                     u32x4 o; o.x = ow[0]; o.y = ow[1]; o.z = ow[2]; o.w = ow[3];
;                     ST_OUT((u32x4*)(dst + (size_t)row * pitch + bj * bjstep), o);
.LBB0_464:
	s_mov_b32 s57, s89
	v_cvt_pk_bf16_f32 v66, v74, v75
	v_cvt_pk_bf16_f32 v67, v68, v69
	v_cvt_pk_bf16_f32 v68, v70, v71
	v_cvt_pk_bf16_f32 v69, v64, v65
	v_lshl_add_u64 v[64:65], v[72:73], 0, s[56:57]
	global_store_dwordx4 v[64:65], v[66:69], off nt
	v_mov_b32_e32 v64, v216
	v_mov_b32_e32 v65, v217
	s_and_b64 vcc, exec, s[40:41]
	v_ffbh_u32_e32 v66, v65
	v_min_u32_e32 v66, 32, v66
	v_lshlrev_b64 v[64:65], v66, v[64:65]
	v_min_u32_e32 v64, 1, v64
	v_or_b32_e32 v64, v65, v64
	v_cvt_f32_u32_e32 v64, v64
	v_sub_u32_e32 v65, 32, v66
	v_ldexp_f32 v64, v64, v65
	v_fmamk_f32 v64, v64, 0x2e000000, v176
	v_mul_f32_e32 v65, 0x4b800000, v64
	v_cmp_gt_f32_e64 s[0:1], s7, v64
	s_nop 1
	v_cndmask_b32_e64 v64, v64, v65, s[0:1]
	v_rsq_f32_e32 v64, v64
	s_nop 0
	v_mul_f32_e32 v65, 0x45800000, v64
	v_cndmask_b32_e64 v66, v64, v65, s[0:1]
	v_mov_b32_e32 v67, v66
	s_mov_b64 s[0:1], -1
	s_cbranch_vccz .LBB0_593
	v_mul_f32_e32 v64, 0xbfb8aa3b, v66
	s_andn2_b64 vcc, exec, s[0:1]
	v_mov_b32_e32 v65, v64
	s_cbranch_vccz .LBB0_594

; __device__ __forceinline__ unsigned pk2(float lo, float hi) { const f32v2_t v = {lo, hi}; const bf16v2_t b = __builtin_convertvector(v, bf16v2_t); return __builtin_bit_cast(unsigned, b); }
; #define ST_OUT(p, v) __builtin_nontemporal_store((v), (p))
;     __device__ __forceinline__ void operator()(AccRef acc, const Unit& u, int wr, int wc, int fr, int fq) const {
;     ...
;                 const int row = row0 + ai * HALF + m * 16;
;                 const float rinv = rsqrtf((float)rss[row] * (1.f / (16777216.f * DM)) + EPS);
;                 const float nrl = rinv * -1.4426950408889634f;
; #pragma unroll
;                 for (int bj = 0; bj < 2; ++bj) {
;                     unsigned ow[4];
; #pragma unroll
;                     for (int n = 0; n < 2; ++n)
; #pragma unroll
;                         for (int jp = 0; jp < 2; ++jp) {
;                             const f32v2_t av = {acc[ai][bj][m][n][2 * jp], acc[ai][bj][m][n][2 * jp + 1]};
;                             f32v2_t hv;
;                             if (sg) { const f32v2_t t = av * nrl; f32v2_t e; e.x = __builtin_amdgcn_exp2f(t.x); e.y = __builtin_amdgcn_exp2f(t.y); const f32v2_t d = e + 1.0f;
;                                 hv.x = __builtin_amdgcn_rcpf(d.x); hv.y = __builtin_amdgcn_rcpf(d.y); }
;                             else hv = av * rinv;
;                             ow[n * 2 + jp] = pk2(hv.x, hv.y);
;                         }
;                     u32x4 o; o.x = ow[0]; o.y = ow[1]; o.z = ow[2]; o.w = ow[3];
;                     ST_OUT((u32x4*)(dst + (size_t)row * pitch + bj * bjstep), o);
.LBB0_482:
	s_mov_b32 s57, s89
	v_cvt_pk_bf16_f32 v50, v58, v59
	v_cvt_pk_bf16_f32 v51, v52, v53
	v_cvt_pk_bf16_f32 v52, v54, v55
	v_cvt_pk_bf16_f32 v53, v48, v49
	v_lshl_add_u64 v[48:49], v[56:57], 0, s[56:57]
	global_store_dwordx4 v[48:49], v[50:53], off nt
	v_mov_b32_e32 v48, v218
	v_mov_b32_e32 v49, v219
	s_and_b64 vcc, exec, s[40:41]
	v_ffbh_u32_e32 v50, v49
	v_min_u32_e32 v50, 32, v50
	v_lshlrev_b64 v[48:49], v50, v[48:49]
	v_min_u32_e32 v48, 1, v48
	v_or_b32_e32 v48, v49, v48
	v_cvt_f32_u32_e32 v48, v48
	v_sub_u32_e32 v49, 32, v50
	v_ldexp_f32 v48, v48, v49
	v_fmamk_f32 v48, v48, 0x2e000000, v176
	v_mul_f32_e32 v49, 0x4b800000, v48
	v_cmp_gt_f32_e64 s[0:1], s7, v48
	s_nop 1
	v_cndmask_b32_e64 v48, v48, v49, s[0:1]
	v_rsq_f32_e32 v48, v48
	s_nop 0
	v_mul_f32_e32 v49, 0x45800000, v48
	v_cndmask_b32_e64 v50, v48, v49, s[0:1]
	v_mov_b32_e32 v51, v50
	s_mov_b64 s[0:1], -1
	s_cbranch_vccz .LBB0_607
	v_mul_f32_e32 v48, 0xbfb8aa3b, v50
	s_andn2_b64 vcc, exec, s[0:1]
	v_mov_b32_e32 v49, v48
	s_cbranch_vccz .LBB0_608

; __device__ __forceinline__ unsigned pk2(float lo, float hi) { const f32v2_t v = {lo, hi}; const bf16v2_t b = __builtin_convertvector(v, bf16v2_t); return __builtin_bit_cast(unsigned, b); }
; #define ST_OUT(p, v) __builtin_nontemporal_store((v), (p))
;     __device__ __forceinline__ void operator()(AccRef acc, const Unit& u, int wr, int wc, int fr, int fq) const {
;     ...
;                 const int row = row0 + ai * HALF + m * 16;
;                 const float rinv = rsqrtf((float)rss[row] * (1.f / (16777216.f * DM)) + EPS);
;                 const float nrl = rinv * -1.4426950408889634f;
; #pragma unroll
;                 for (int bj = 0; bj < 2; ++bj) {
;                     unsigned ow[4];
; #pragma unroll
;                     for (int n = 0; n < 2; ++n)
; #pragma unroll
;                         for (int jp = 0; jp < 2; ++jp) {
;                             const f32v2_t av = {acc[ai][bj][m][n][2 * jp], acc[ai][bj][m][n][2 * jp + 1]};
;                             f32v2_t hv;
;                             if (sg) { const f32v2_t t = av * nrl; f32v2_t e; e.x = __builtin_amdgcn_exp2f(t.x); e.y = __builtin_amdgcn_exp2f(t.y); const f32v2_t d = e + 1.0f;
;                                 hv.x = __builtin_amdgcn_rcpf(d.x); hv.y = __builtin_amdgcn_rcpf(d.y); }
;                             else hv = av * rinv;
;                             ow[n * 2 + jp] = pk2(hv.x, hv.y);
;                         }
;                     u32x4 o; o.x = ow[0]; o.y = ow[1]; o.z = ow[2]; o.w = ow[3];
;                     ST_OUT((u32x4*)(dst + (size_t)row * pitch + bj * bjstep), o);
.LBB0_500:
	s_mov_b32 s57, s89
	v_cvt_pk_bf16_f32 v34, v42, v43
	v_cvt_pk_bf16_f32 v35, v36, v37
	v_cvt_pk_bf16_f32 v36, v38, v39
	v_cvt_pk_bf16_f32 v37, v32, v33
	v_lshl_add_u64 v[32:33], v[40:41], 0, s[56:57]
	global_store_dwordx4 v[32:33], v[34:37], off nt
	v_mov_b32_e32 v32, v220
	v_mov_b32_e32 v33, v221
	s_and_b64 vcc, exec, s[40:41]
	v_ffbh_u32_e32 v34, v33
	v_min_u32_e32 v34, 32, v34
	v_lshlrev_b64 v[32:33], v34, v[32:33]
	v_min_u32_e32 v32, 1, v32
	v_or_b32_e32 v32, v33, v32
	v_cvt_f32_u32_e32 v32, v32
	v_sub_u32_e32 v33, 32, v34
	v_ldexp_f32 v32, v32, v33
	v_fmamk_f32 v32, v32, 0x2e000000, v176
	v_mul_f32_e32 v33, 0x4b800000, v32
	v_cmp_gt_f32_e64 s[0:1], s7, v32
	s_nop 1
	v_cndmask_b32_e64 v32, v32, v33, s[0:1]
	v_rsq_f32_e32 v32, v32
	s_nop 0
	v_mul_f32_e32 v33, 0x45800000, v32
	v_cndmask_b32_e64 v34, v32, v33, s[0:1]
	v_mov_b32_e32 v35, v34
	s_mov_b64 s[0:1], -1
	s_cbranch_vccz .LBB0_621
	v_mul_f32_e32 v32, 0xbfb8aa3b, v34
	s_andn2_b64 vcc, exec, s[0:1]
	v_mov_b32_e32 v33, v32
	s_cbranch_vccz .LBB0_622

; __device__ __forceinline__ unsigned pk2(float lo, float hi) { const f32v2_t v = {lo, hi}; const bf16v2_t b = __builtin_convertvector(v, bf16v2_t); return __builtin_bit_cast(unsigned, b); }
; #define ST_OUT(p, v) __builtin_nontemporal_store((v), (p))
;     __device__ __forceinline__ void operator()(AccRef acc, const Unit& u, int wr, int wc, int fr, int fq) const {
;     ...
;                 const int row = row0 + ai * HALF + m * 16;
;                 const float rinv = rsqrtf((float)rss[row] * (1.f / (16777216.f * DM)) + EPS);
;                 const float nrl = rinv * -1.4426950408889634f;
; #pragma unroll
;                 for (int bj = 0; bj < 2; ++bj) {
;                     unsigned ow[4];
; #pragma unroll
;                     for (int n = 0; n < 2; ++n)
; #pragma unroll
;                         for (int jp = 0; jp < 2; ++jp) {
;                             const f32v2_t av = {acc[ai][bj][m][n][2 * jp], acc[ai][bj][m][n][2 * jp + 1]};
;                             f32v2_t hv;
;                             if (sg) { const f32v2_t t = av * nrl; f32v2_t e; e.x = __builtin_amdgcn_exp2f(t.x); e.y = __builtin_amdgcn_exp2f(t.y); const f32v2_t d = e + 1.0f;
;                                 hv.x = __builtin_amdgcn_rcpf(d.x); hv.y = __builtin_amdgcn_rcpf(d.y); }
;                             else hv = av * rinv;
;                             ow[n * 2 + jp] = pk2(hv.x, hv.y);
;                         }
;                     u32x4 o; o.x = ow[0]; o.y = ow[1]; o.z = ow[2]; o.w = ow[3];
;                     ST_OUT((u32x4*)(dst + (size_t)row * pitch + bj * bjstep), o);
.LBB0_518:
	s_mov_b32 s57, s89
	v_cvt_pk_bf16_f32 v18, v26, v27
	v_cvt_pk_bf16_f32 v19, v20, v21
	v_cvt_pk_bf16_f32 v20, v22, v23
	v_cvt_pk_bf16_f32 v21, v16, v17
	v_lshl_add_u64 v[16:17], v[24:25], 0, s[56:57]
	global_store_dwordx4 v[16:17], v[18:21], off nt
	v_mov_b32_e32 v16, v222
	v_mov_b32_e32 v17, v223
	s_and_b64 vcc, exec, s[40:41]
	v_ffbh_u32_e32 v18, v17
	v_min_u32_e32 v18, 32, v18
	v_lshlrev_b64 v[16:17], v18, v[16:17]
	v_min_u32_e32 v16, 1, v16
	v_or_b32_e32 v16, v17, v16
	v_cvt_f32_u32_e32 v16, v16
	v_sub_u32_e32 v17, 32, v18
	v_ldexp_f32 v16, v16, v17
	v_fmamk_f32 v16, v16, 0x2e000000, v176
	v_mul_f32_e32 v17, 0x4b800000, v16
	v_cmp_gt_f32_e64 s[0:1], s7, v16
	s_nop 1
	v_cndmask_b32_e64 v16, v16, v17, s[0:1]
	v_rsq_f32_e32 v16, v16
	s_nop 0
	v_mul_f32_e32 v17, 0x45800000, v16
	v_cndmask_b32_e64 v18, v16, v17, s[0:1]
	v_mov_b32_e32 v19, v18
	s_mov_b64 s[0:1], -1
	s_cbranch_vccz .LBB0_635
	v_mul_f32_e32 v16, 0xbfb8aa3b, v18
	s_andn2_b64 vcc, exec, s[0:1]
	v_mov_b32_e32 v17, v16
	s_cbranch_vccz .LBB0_636

; __device__ __forceinline__ unsigned pk2(float lo, float hi) { const f32v2_t v = {lo, hi}; const bf16v2_t b = __builtin_convertvector(v, bf16v2_t); return __builtin_bit_cast(unsigned, b); }
; #define ST_OUT(p, v) __builtin_nontemporal_store((v), (p))
;     __device__ __forceinline__ void operator()(AccRef acc, const Unit& u, int wr, int wc, int fr, int fq) const {
;         const int row0 = u.pm * BM + wr * 64 + fr, col0 = u.pn * 128 + wc * 32 + 8 * fq;
; #pragma unroll
;         for (int ai = 0; ai < 2; ++ai)
; #pragma unroll
;             for (int m = 0; m < 4; ++m) {
;                 const int row = row0 + ai * HALF + m * 16;
;                 const float rinv = rsqrtf((float)rss[row] * (1.f / (16777216.f * DM)) + EPS);
;                 const float nrl = rinv * -1.4426950408889634f, r2 = rinv * rinv;
;                 unsigned ow[4];
; #pragma unroll
;                 for (int n = 0; n < 2; ++n)
; #pragma unroll
;                     for (int jp = 0; jp < 2; ++jp) {
;                         const f32v2_t ag = {acc[ai][0][m][n][2 * jp], acc[ai][0][m][n][2 * jp + 1]}, au = {acc[ai][1][m][n][2 * jp], acc[ai][1][m][n][2 * jp + 1]};
;                         const f32v2_t t = ag * nrl;
;                         f32v2_t e; e.x = __builtin_amdgcn_exp2f(t.x); e.y = __builtin_amdgcn_exp2f(t.y);
;                         const f32v2_t d = e + 1.0f;
;                         f32v2_t r; r.x = __builtin_amdgcn_rcpf(d.x); r.y = __builtin_amdgcn_rcpf(d.y);
;                         const f32v2_t hv = (ag * au) * (r * r2);
;                         ow[n * 2 + jp] = pk2(hv.x, hv.y);
;                     }
;                 u32x4 o; o.x = ow[0]; o.y = ow[1]; o.z = ow[2]; o.w = ow[3];
;                 ST_OUT((u32x4*)(H + (size_t)row * FF + col0), o);
.LBB0_748:
	v_lshl_add_u32 v156, s27, 8, v162
	v_ashrrev_i32_e32 v157, 31, v156
	v_lshl_add_u64 v[158:159], v[156:157], 3, s[40:41]
	global_load_dwordx2 v[166:167], v[158:159], off
	global_load_dwordx2 v[206:207], v[158:159], off offset:128
	global_load_dwordx2 v[208:209], v[158:159], off offset:256
	global_load_dwordx2 v[210:211], v[158:159], off offset:384
	global_load_dwordx2 v[212:213], v[158:159], off offset:1024
	global_load_dwordx2 v[214:215], v[158:159], off offset:1152
	global_load_dwordx2 v[216:217], v[158:159], off offset:1280
	global_load_dwordx2 v[218:219], v[158:159], off offset:1408
	v_pk_mul_f32 v[120:121], v[124:125], v[120:121]
	v_pk_mul_f32 v[122:123], v[126:127], v[122:123]
	v_pk_mul_f32 v[112:113], v[116:117], v[112:113]
	v_pk_mul_f32 v[114:115], v[118:119], v[114:115]
	v_readlane_b32 s16, v253, 42
	v_lshl_or_b32 v160, s20, 7, v164
	v_readlane_b32 s17, v253, 43
	v_ashrrev_i32_e32 v161, 31, v160
	v_pk_mul_f32 v[104:105], v[108:109], v[104:105]
	v_pk_mul_f32 v[106:107], v[110:111], v[106:107]
	v_pk_mul_f32 v[96:97], v[100:101], v[96:97]
	v_pk_mul_f32 v[98:99], v[102:103], v[98:99]
	v_pk_mul_f32 v[88:89], v[92:93], v[88:89]
	v_pk_mul_f32 v[90:91], v[94:95], v[90:91]
	v_pk_mul_f32 v[80:81], v[84:85], v[80:81]
	v_pk_mul_f32 v[82:83], v[86:87], v[82:83]
	v_pk_mul_f32 v[72:73], v[76:77], v[72:73]
	v_pk_mul_f32 v[74:75], v[78:79], v[74:75]
	v_pk_mul_f32 v[64:65], v[68:69], v[64:65]
	v_pk_mul_f32 v[66:67], v[70:71], v[66:67]
	v_pk_mul_f32 v[56:57], v[60:61], v[56:57]
	v_pk_mul_f32 v[58:59], v[62:63], v[58:59]
	v_pk_mul_f32 v[48:49], v[52:53], v[48:49]
	v_pk_mul_f32 v[50:51], v[54:55], v[50:51]
	v_pk_mul_f32 v[40:41], v[44:45], v[40:41]
	v_pk_mul_f32 v[42:43], v[46:47], v[42:43]
	v_pk_mul_f32 v[32:33], v[36:37], v[32:33]
	v_pk_mul_f32 v[34:35], v[38:39], v[34:35]
	v_pk_mul_f32 v[24:25], v[28:29], v[24:25]
	v_pk_mul_f32 v[26:27], v[30:31], v[26:27]
	v_pk_mul_f32 v[16:17], v[20:21], v[16:17]
	v_pk_mul_f32 v[18:19], v[22:23], v[18:19]
	v_pk_mul_f32 v[8:9], v[12:13], v[8:9]
	v_pk_mul_f32 v[10:11], v[14:15], v[10:11]
	v_pk_mul_f32 v[0:1], v[4:5], v[0:1]
	v_pk_mul_f32 v[2:3], v[6:7], v[2:3]
	s_movk_i32 s92, 0x37ff
	s_waitcnt vmcnt(0)
	v_ffbh_u32_e32 v157, v167
	v_min_u32_e32 v157, 32, v157
	v_lshlrev_b64 v[166:167], v157, v[166:167]
	v_min_u32_e32 v166, 1, v166
	v_or_b32_e32 v166, v167, v166
	v_cvt_f32_u32_e32 v166, v166
	v_sub_u32_e32 v157, 32, v157
	v_ldexp_f32 v157, v166, v157
	v_fmamk_f32 v157, v157, 0x2e000000, v176
	v_cmp_gt_f32_e32 vcc, s7, v157
	v_mul_f32_e32 v166, 0x4b800000, v157
	s_nop 0
	v_cndmask_b32_e32 v157, v157, v166, vcc
	v_rsq_f32_e32 v157, v157
	s_nop 0
	v_mul_f32_e32 v166, 0x45800000, v157
	v_cndmask_b32_e32 v157, v157, v166, vcc
	v_mul_f32_e32 v166, 0xbfb8aa3b, v157
	v_pk_mul_f32 v[170:171], v[124:125], v[166:167] op_sel_hi:[1,0]
	v_mul_f32_e32 v168, v157, v157
	v_exp_f32_e32 v170, v170
	v_exp_f32_e32 v171, v171
	s_nop 0
	v_pk_add_f32 v[170:171], v[170:171], 1.0 op_sel_hi:[1,0]
	s_nop 0
	v_rcp_f32_e32 v170, v170
	v_rcp_f32_e32 v171, v171
	s_nop 0
	v_pk_mul_f32 v[124:125], v[168:169], v[170:171] op_sel_hi:[0,1]
	v_pk_mul_f32 v[120:121], v[120:121], v[124:125]
	v_pk_mul_f32 v[124:125], v[126:127], v[166:167] op_sel_hi:[1,0]
	v_cvt_pk_bf16_f32 v120, v120, v121
	v_exp_f32_e32 v124, v124
	v_exp_f32_e32 v125, v125
	s_nop 0
	v_pk_add_f32 v[124:125], v[124:125], 1.0 op_sel_hi:[1,0]
	s_nop 0
	v_rcp_f32_e32 v124, v124
	v_rcp_f32_e32 v125, v125
	s_nop 0
	v_pk_mul_f32 v[124:125], v[168:169], v[124:125] op_sel_hi:[0,1]
	v_pk_mul_f32 v[122:123], v[122:123], v[124:125]
	s_nop 0
	v_cvt_pk_bf16_f32 v121, v122, v123
	v_pk_mul_f32 v[122:123], v[116:117], v[166:167] op_sel_hi:[1,0]
	s_nop 0
	v_exp_f32_e32 v122, v122
	v_exp_f32_e32 v123, v123
	s_nop 0
	v_pk_add_f32 v[122:123], v[122:123], 1.0 op_sel_hi:[1,0]
	s_nop 0
	v_rcp_f32_e32 v122, v122
	v_rcp_f32_e32 v123, v123
	s_nop 0
	v_pk_mul_f32 v[116:117], v[168:169], v[122:123] op_sel_hi:[0,1]
	v_pk_mul_f32 v[112:113], v[112:113], v[116:117]
	s_nop 0
	v_cvt_pk_bf16_f32 v122, v112, v113
	v_pk_mul_f32 v[112:113], v[118:119], v[166:167] op_sel_hi:[1,0]
	v_or_b32_e32 v119, 16, v156
	v_exp_f32_e32 v112, v112
	v_exp_f32_e32 v113, v113
	s_nop 0
	v_pk_add_f32 v[112:113], v[112:113], 1.0 op_sel_hi:[1,0]
	s_nop 0
	v_rcp_f32_e32 v112, v112
	v_rcp_f32_e32 v113, v113
	s_nop 0
	v_pk_mul_f32 v[112:113], v[168:169], v[112:113] op_sel_hi:[0,1]
	v_pk_mul_f32 v[112:113], v[114:115], v[112:113]
	v_lshlrev_b64 v[114:115], 1, v[160:161]
	v_cvt_pk_bf16_f32 v123, v112, v113
	v_mov_b64_e32 v[112:113], s[16:17]
	v_mad_i64_i32 v[116:117], s[22:23], v156, s6, v[112:113]
	v_lshl_add_u64 v[116:117], v[116:117], 0, v[114:115]
	global_store_dwordx4 v[116:117], v[120:123], off nt
	v_mov_b32_e32 v116, v206
	v_mov_b32_e32 v117, v207
	v_ffbh_u32_e32 v118, v117
	v_min_u32_e32 v118, 32, v118
	v_lshlrev_b64 v[116:117], v118, v[116:117]
	v_min_u32_e32 v116, 1, v116
	v_or_b32_e32 v116, v117, v116
	v_cvt_f32_u32_e32 v116, v116
	v_sub_u32_e32 v117, 32, v118
	v_ldexp_f32 v116, v116, v117
	v_fmamk_f32 v116, v116, 0x2e000000, v176
	v_cmp_gt_f32_e32 vcc, s7, v116
	v_mul_f32_e32 v117, 0x4b800000, v116
	s_nop 0
	v_cndmask_b32_e32 v116, v116, v117, vcc
	v_rsq_f32_e32 v116, v116
	s_nop 0
	v_mul_f32_e32 v117, 0x45800000, v116
	v_cndmask_b32_e32 v117, v116, v117, vcc
	v_mul_f32_e32 v116, 0xbfb8aa3b, v117
	v_pk_mul_f32 v[120:121], v[108:109], v[116:117] op_sel_hi:[1,0]
	v_mul_f32_e32 v118, v117, v117
	v_exp_f32_e32 v120, v120
	v_exp_f32_e32 v121, v121
	s_nop 0
	v_pk_add_f32 v[120:121], v[120:121], 1.0 op_sel_hi:[1,0]
	s_nop 0
	v_rcp_f32_e32 v120, v120
	v_rcp_f32_e32 v121, v121
	s_nop 0
	v_pk_mul_f32 v[108:109], v[118:119], v[120:121] op_sel_hi:[0,1]
; __device__ __forceinline__ unsigned pk2(float lo, float hi) { const f32v2_t v = {lo, hi}; const bf16v2_t b = __builtin_convertvector(v, bf16v2_t); return __builtin_bit_cast(unsigned, b); }
; #define ST_OUT(p, v) __builtin_nontemporal_store((v), (p))
;     __device__ __forceinline__ void operator()(AccRef acc, const Unit& u, int wr, int wc, int fr, int fq) const {
;     ...
;             for (int m = 0; m < 4; ++m) {
;                 const int row = row0 + ai * HALF + m * 16;
;                 const float rinv = rsqrtf((float)rss[row] * (1.f / (16777216.f * DM)) + EPS);
;                 const float nrl = rinv * -1.4426950408889634f, r2 = rinv * rinv;
;                 unsigned ow[4];
; #pragma unroll
;                 for (int n = 0; n < 2; ++n)
; #pragma unroll
;                     for (int jp = 0; jp < 2; ++jp) {
;                         const f32v2_t ag = {acc[ai][0][m][n][2 * jp], acc[ai][0][m][n][2 * jp + 1]}, au = {acc[ai][1][m][n][2 * jp], acc[ai][1][m][n][2 * jp + 1]};
;                         const f32v2_t t = ag * nrl;
;                         f32v2_t e; e.x = __builtin_amdgcn_exp2f(t.x); e.y = __builtin_amdgcn_exp2f(t.y);
;                         const f32v2_t d = e + 1.0f;
;                         f32v2_t r; r.x = __builtin_amdgcn_rcpf(d.x); r.y = __builtin_amdgcn_rcpf(d.y);
;                         const f32v2_t hv = (ag * au) * (r * r2);
;                         ow[n * 2 + jp] = pk2(hv.x, hv.y);
;                     }
;                 u32x4 o; o.x = ow[0]; o.y = ow[1]; o.z = ow[2]; o.w = ow[3];
;                 ST_OUT((u32x4*)(H + (size_t)row * FF + col0), o);
	v_pk_mul_f32 v[104:105], v[104:105], v[108:109]
	v_pk_mul_f32 v[108:109], v[110:111], v[116:117] op_sel_hi:[1,0]
	v_cvt_pk_bf16_f32 v104, v104, v105
	v_exp_f32_e32 v108, v108
	v_exp_f32_e32 v109, v109
	s_nop 0
	v_pk_add_f32 v[108:109], v[108:109], 1.0 op_sel_hi:[1,0]
	s_nop 0
	v_rcp_f32_e32 v108, v108
	v_rcp_f32_e32 v109, v109
	s_nop 0
	v_pk_mul_f32 v[108:109], v[118:119], v[108:109] op_sel_hi:[0,1]
	v_pk_mul_f32 v[106:107], v[106:107], v[108:109]
	s_nop 0
	v_cvt_pk_bf16_f32 v105, v106, v107
	v_pk_mul_f32 v[106:107], v[100:101], v[116:117] op_sel_hi:[1,0]
	s_nop 0
	v_exp_f32_e32 v106, v106
	v_exp_f32_e32 v107, v107
	s_nop 0
	v_pk_add_f32 v[106:107], v[106:107], 1.0 op_sel_hi:[1,0]
	s_nop 0
	v_rcp_f32_e32 v106, v106
	v_rcp_f32_e32 v107, v107
	s_nop 0
	v_pk_mul_f32 v[100:101], v[118:119], v[106:107] op_sel_hi:[0,1]
	v_pk_mul_f32 v[96:97], v[96:97], v[100:101]
	s_nop 0
	v_cvt_pk_bf16_f32 v106, v96, v97
	v_pk_mul_f32 v[96:97], v[102:103], v[116:117] op_sel_hi:[1,0]
	s_nop 0
	v_exp_f32_e32 v96, v96
	v_exp_f32_e32 v97, v97
	s_nop 0
	v_pk_add_f32 v[96:97], v[96:97], 1.0 op_sel_hi:[1,0]
	s_nop 0
	v_rcp_f32_e32 v96, v96
	v_rcp_f32_e32 v97, v97
	s_nop 0
	v_pk_mul_f32 v[96:97], v[118:119], v[96:97] op_sel_hi:[0,1]
	v_pk_mul_f32 v[96:97], v[98:99], v[96:97]
	v_or_b32_e32 v99, 32, v156
	v_cvt_pk_bf16_f32 v107, v96, v97
	v_mad_i64_i32 v[96:97], s[22:23], v119, s6, v[112:113]
	v_lshl_add_u64 v[96:97], v[96:97], 0, v[114:115]
	global_store_dwordx4 v[96:97], v[104:107], off nt
	v_mov_b32_e32 v96, v208
	v_mov_b32_e32 v97, v209
	v_ffbh_u32_e32 v98, v97
	v_min_u32_e32 v98, 32, v98
	v_lshlrev_b64 v[96:97], v98, v[96:97]
	v_min_u32_e32 v96, 1, v96
	v_or_b32_e32 v96, v97, v96
	v_cvt_f32_u32_e32 v96, v96
	v_sub_u32_e32 v97, 32, v98
	v_ldexp_f32 v96, v96, v97
	v_fmamk_f32 v96, v96, 0x2e000000, v176
	v_cmp_gt_f32_e32 vcc, s7, v96
	v_mul_f32_e32 v97, 0x4b800000, v96
	s_nop 0
	v_cndmask_b32_e32 v96, v96, v97, vcc
	v_rsq_f32_e32 v96, v96
	s_nop 0
	v_mul_f32_e32 v97, 0x45800000, v96
	v_cndmask_b32_e32 v97, v96, v97, vcc
	v_mul_f32_e32 v96, 0xbfb8aa3b, v97
	v_pk_mul_f32 v[100:101], v[92:93], v[96:97] op_sel_hi:[1,0]
	v_mul_f32_e32 v98, v97, v97
	v_exp_f32_e32 v100, v100
	v_exp_f32_e32 v101, v101
	s_nop 0
	v_pk_add_f32 v[100:101], v[100:101], 1.0 op_sel_hi:[1,0]
	s_nop 0
	v_rcp_f32_e32 v100, v100
	v_rcp_f32_e32 v101, v101
	s_nop 0
	v_pk_mul_f32 v[92:93], v[98:99], v[100:101] op_sel_hi:[0,1]
	v_pk_mul_f32 v[88:89], v[88:89], v[92:93]
	v_pk_mul_f32 v[92:93], v[94:95], v[96:97] op_sel_hi:[1,0]
	v_cvt_pk_bf16_f32 v88, v88, v89
	v_exp_f32_e32 v92, v92
	v_exp_f32_e32 v93, v93
	s_nop 0
	v_pk_add_f32 v[92:93], v[92:93], 1.0 op_sel_hi:[1,0]
	s_nop 0
	v_rcp_f32_e32 v92, v92
	v_rcp_f32_e32 v93, v93
	s_nop 0
	v_pk_mul_f32 v[92:93], v[98:99], v[92:93] op_sel_hi:[0,1]
	v_pk_mul_f32 v[90:91], v[90:91], v[92:93]
	s_nop 0
	v_cvt_pk_bf16_f32 v89, v90, v91
	v_pk_mul_f32 v[90:91], v[84:85], v[96:97] op_sel_hi:[1,0]
	s_nop 0
	v_exp_f32_e32 v90, v90
	v_exp_f32_e32 v91, v91
	s_nop 0
	v_pk_add_f32 v[90:91], v[90:91], 1.0 op_sel_hi:[1,0]
	s_nop 0
	v_rcp_f32_e32 v90, v90
	v_rcp_f32_e32 v91, v91
	s_nop 0
	v_pk_mul_f32 v[84:85], v[98:99], v[90:91] op_sel_hi:[0,1]
	v_pk_mul_f32 v[80:81], v[80:81], v[84:85]
	s_nop 0
	v_cvt_pk_bf16_f32 v90, v80, v81
	v_pk_mul_f32 v[80:81], v[86:87], v[96:97] op_sel_hi:[1,0]
	s_nop 0
	v_exp_f32_e32 v80, v80
	v_exp_f32_e32 v81, v81
	s_nop 0
	v_pk_add_f32 v[80:81], v[80:81], 1.0 op_sel_hi:[1,0]
	s_nop 0
	v_rcp_f32_e32 v80, v80
	v_rcp_f32_e32 v81, v81
	s_nop 0
	v_pk_mul_f32 v[80:81], v[98:99], v[80:81] op_sel_hi:[0,1]
	v_pk_mul_f32 v[80:81], v[82:83], v[80:81]
	v_or_b32_e32 v83, 48, v156
	v_cvt_pk_bf16_f32 v91, v80, v81
	v_mad_i64_i32 v[80:81], s[22:23], v99, s6, v[112:113]
	v_lshl_add_u64 v[80:81], v[80:81], 0, v[114:115]
	global_store_dwordx4 v[80:81], v[88:91], off nt
	v_mov_b32_e32 v80, v210
	v_mov_b32_e32 v81, v211
	v_ffbh_u32_e32 v82, v81
	v_min_u32_e32 v82, 32, v82
	v_lshlrev_b64 v[80:81], v82, v[80:81]
	v_min_u32_e32 v80, 1, v80
	v_or_b32_e32 v80, v81, v80
	v_cvt_f32_u32_e32 v80, v80
	v_sub_u32_e32 v81, 32, v82
	v_ldexp_f32 v80, v80, v81
	v_fmamk_f32 v80, v80, 0x2e000000, v176
	v_cmp_gt_f32_e32 vcc, s7, v80
	v_mul_f32_e32 v81, 0x4b800000, v80
	s_nop 0
	v_cndmask_b32_e32 v80, v80, v81, vcc
	v_rsq_f32_e32 v80, v80
	s_nop 0
	v_mul_f32_e32 v81, 0x45800000, v80
	v_cndmask_b32_e32 v81, v80, v81, vcc
	v_mul_f32_e32 v80, 0xbfb8aa3b, v81
	v_pk_mul_f32 v[84:85], v[76:77], v[80:81] op_sel_hi:[1,0]
	v_mul_f32_e32 v82, v81, v81
	v_exp_f32_e32 v84, v84
	v_exp_f32_e32 v85, v85
	s_nop 0
	v_pk_add_f32 v[84:85], v[84:85], 1.0 op_sel_hi:[1,0]
	s_nop 0
	v_rcp_f32_e32 v84, v84
	v_rcp_f32_e32 v85, v85
	s_nop 0
	v_pk_mul_f32 v[76:77], v[82:83], v[84:85] op_sel_hi:[0,1]
	v_pk_mul_f32 v[72:73], v[72:73], v[76:77]
	v_pk_mul_f32 v[76:77], v[78:79], v[80:81] op_sel_hi:[1,0]
	v_cvt_pk_bf16_f32 v72, v72, v73
	v_exp_f32_e32 v76, v76
	v_exp_f32_e32 v77, v77
	s_nop 0
	v_pk_add_f32 v[76:77], v[76:77], 1.0 op_sel_hi:[1,0]
	s_nop 0
	v_rcp_f32_e32 v76, v76
	v_rcp_f32_e32 v77, v77
	s_nop 0
	v_pk_mul_f32 v[76:77], v[82:83], v[76:77] op_sel_hi:[0,1]
	v_pk_mul_f32 v[74:75], v[74:75], v[76:77]
	s_nop 0
	v_cvt_pk_bf16_f32 v73, v74, v75
	v_pk_mul_f32 v[74:75], v[68:69], v[80:81] op_sel_hi:[1,0]
	s_nop 0
	v_exp_f32_e32 v74, v74
	v_exp_f32_e32 v75, v75
	s_nop 0
	v_pk_add_f32 v[74:75], v[74:75], 1.0 op_sel_hi:[1,0]
	s_nop 0
	v_rcp_f32_e32 v74, v74
	v_rcp_f32_e32 v75, v75
	s_nop 0
	v_pk_mul_f32 v[68:69], v[82:83], v[74:75] op_sel_hi:[0,1]
	v_pk_mul_f32 v[64:65], v[64:65], v[68:69]
	s_nop 0
	v_cvt_pk_bf16_f32 v74, v64, v65
	v_pk_mul_f32 v[64:65], v[70:71], v[80:81] op_sel_hi:[1,0]
	s_nop 0
	v_exp_f32_e32 v64, v64
; __device__ __forceinline__ unsigned pk2(float lo, float hi) { const f32v2_t v = {lo, hi}; const bf16v2_t b = __builtin_convertvector(v, bf16v2_t); return __builtin_bit_cast(unsigned, b); }
; #define ST_OUT(p, v) __builtin_nontemporal_store((v), (p))
;     __device__ __forceinline__ void operator()(AccRef acc, const Unit& u, int wr, int wc, int fr, int fq) const {
;     ...
;             for (int m = 0; m < 4; ++m) {
;                 const int row = row0 + ai * HALF + m * 16;
;                 const float rinv = rsqrtf((float)rss[row] * (1.f / (16777216.f * DM)) + EPS);
;                 const float nrl = rinv * -1.4426950408889634f, r2 = rinv * rinv;
;                 unsigned ow[4];
; #pragma unroll
;                 for (int n = 0; n < 2; ++n)
; #pragma unroll
;                     for (int jp = 0; jp < 2; ++jp) {
;                         const f32v2_t ag = {acc[ai][0][m][n][2 * jp], acc[ai][0][m][n][2 * jp + 1]}, au = {acc[ai][1][m][n][2 * jp], acc[ai][1][m][n][2 * jp + 1]};
;                         const f32v2_t t = ag * nrl;
;                         f32v2_t e; e.x = __builtin_amdgcn_exp2f(t.x); e.y = __builtin_amdgcn_exp2f(t.y);
;                         const f32v2_t d = e + 1.0f;
;                         f32v2_t r; r.x = __builtin_amdgcn_rcpf(d.x); r.y = __builtin_amdgcn_rcpf(d.y);
;                         const f32v2_t hv = (ag * au) * (r * r2);
;                         ow[n * 2 + jp] = pk2(hv.x, hv.y);
;                     }
;                 u32x4 o; o.x = ow[0]; o.y = ow[1]; o.z = ow[2]; o.w = ow[3];
;                 ST_OUT((u32x4*)(H + (size_t)row * FF + col0), o);
	v_exp_f32_e32 v65, v65
	s_nop 0
	v_pk_add_f32 v[64:65], v[64:65], 1.0 op_sel_hi:[1,0]
	s_nop 0
	v_rcp_f32_e32 v64, v64
	v_rcp_f32_e32 v65, v65
	s_nop 0
	v_pk_mul_f32 v[64:65], v[82:83], v[64:65] op_sel_hi:[0,1]
	v_pk_mul_f32 v[64:65], v[66:67], v[64:65]
	v_add_u32_e32 v67, 0x80, v156
	v_cvt_pk_bf16_f32 v75, v64, v65
	v_mad_i64_i32 v[64:65], s[22:23], v83, s6, v[112:113]
	v_lshl_add_u64 v[64:65], v[64:65], 0, v[114:115]
	global_store_dwordx4 v[64:65], v[72:75], off nt
	v_mov_b32_e32 v64, v212
	v_mov_b32_e32 v65, v213
	v_ffbh_u32_e32 v66, v65
	v_min_u32_e32 v66, 32, v66
	v_lshlrev_b64 v[64:65], v66, v[64:65]
	v_min_u32_e32 v64, 1, v64
	v_or_b32_e32 v64, v65, v64
	v_cvt_f32_u32_e32 v64, v64
	v_sub_u32_e32 v65, 32, v66
	v_ldexp_f32 v64, v64, v65
	v_fmamk_f32 v64, v64, 0x2e000000, v176
	v_cmp_gt_f32_e32 vcc, s7, v64
	v_mul_f32_e32 v65, 0x4b800000, v64
	s_nop 0
	v_cndmask_b32_e32 v64, v64, v65, vcc
	v_rsq_f32_e32 v64, v64
	s_nop 0
	v_mul_f32_e32 v65, 0x45800000, v64
	v_cndmask_b32_e32 v65, v64, v65, vcc
	v_mul_f32_e32 v64, 0xbfb8aa3b, v65
	v_pk_mul_f32 v[68:69], v[60:61], v[64:65] op_sel_hi:[1,0]
	v_mul_f32_e32 v66, v65, v65
	v_exp_f32_e32 v68, v68
	v_exp_f32_e32 v69, v69
	s_nop 0
	v_pk_add_f32 v[68:69], v[68:69], 1.0 op_sel_hi:[1,0]
	s_nop 0
	v_rcp_f32_e32 v68, v68
	v_rcp_f32_e32 v69, v69
	s_nop 0
	v_pk_mul_f32 v[60:61], v[66:67], v[68:69] op_sel_hi:[0,1]
	v_pk_mul_f32 v[56:57], v[56:57], v[60:61]
	v_pk_mul_f32 v[60:61], v[62:63], v[64:65] op_sel_hi:[1,0]
	v_cvt_pk_bf16_f32 v56, v56, v57
	v_exp_f32_e32 v60, v60
	v_exp_f32_e32 v61, v61
	s_nop 0
	v_pk_add_f32 v[60:61], v[60:61], 1.0 op_sel_hi:[1,0]
	s_nop 0
	v_rcp_f32_e32 v60, v60
	v_rcp_f32_e32 v61, v61
	s_nop 0
	v_pk_mul_f32 v[60:61], v[66:67], v[60:61] op_sel_hi:[0,1]
	v_pk_mul_f32 v[58:59], v[58:59], v[60:61]
	s_nop 0
	v_cvt_pk_bf16_f32 v57, v58, v59
	v_pk_mul_f32 v[58:59], v[52:53], v[64:65] op_sel_hi:[1,0]
	s_nop 0
	v_exp_f32_e32 v58, v58
	v_exp_f32_e32 v59, v59
	s_nop 0
	v_pk_add_f32 v[58:59], v[58:59], 1.0 op_sel_hi:[1,0]
	s_nop 0
	v_rcp_f32_e32 v58, v58
	v_rcp_f32_e32 v59, v59
	s_nop 0
	v_pk_mul_f32 v[52:53], v[66:67], v[58:59] op_sel_hi:[0,1]
	v_pk_mul_f32 v[48:49], v[48:49], v[52:53]
	s_nop 0
	v_cvt_pk_bf16_f32 v58, v48, v49
	v_pk_mul_f32 v[48:49], v[54:55], v[64:65] op_sel_hi:[1,0]
	s_nop 0
	v_exp_f32_e32 v48, v48
	v_exp_f32_e32 v49, v49
	s_nop 0
	v_pk_add_f32 v[48:49], v[48:49], 1.0 op_sel_hi:[1,0]
	s_nop 0
	v_rcp_f32_e32 v48, v48
	v_rcp_f32_e32 v49, v49
	s_nop 0
	v_pk_mul_f32 v[48:49], v[66:67], v[48:49] op_sel_hi:[0,1]
	v_pk_mul_f32 v[48:49], v[50:51], v[48:49]
	v_add_u32_e32 v51, 0x90, v156
	v_cvt_pk_bf16_f32 v59, v48, v49
	v_mad_i64_i32 v[48:49], s[22:23], v67, s6, v[112:113]
	v_lshl_add_u64 v[48:49], v[48:49], 0, v[114:115]
	global_store_dwordx4 v[48:49], v[56:59], off nt
	v_mov_b32_e32 v48, v214
	v_mov_b32_e32 v49, v215
	v_ffbh_u32_e32 v50, v49
	v_min_u32_e32 v50, 32, v50
	v_lshlrev_b64 v[48:49], v50, v[48:49]
	v_min_u32_e32 v48, 1, v48
	v_or_b32_e32 v48, v49, v48
	v_cvt_f32_u32_e32 v48, v48
	v_sub_u32_e32 v49, 32, v50
	v_ldexp_f32 v48, v48, v49
	v_fmamk_f32 v48, v48, 0x2e000000, v176
	v_cmp_gt_f32_e32 vcc, s7, v48
	v_mul_f32_e32 v49, 0x4b800000, v48
	s_nop 0
	v_cndmask_b32_e32 v48, v48, v49, vcc
	v_rsq_f32_e32 v48, v48
	s_nop 0
	v_mul_f32_e32 v49, 0x45800000, v48
	v_cndmask_b32_e32 v49, v48, v49, vcc
	v_mul_f32_e32 v48, 0xbfb8aa3b, v49
	v_pk_mul_f32 v[52:53], v[44:45], v[48:49] op_sel_hi:[1,0]
	v_mul_f32_e32 v50, v49, v49
	v_exp_f32_e32 v52, v52
	v_exp_f32_e32 v53, v53
	s_nop 0
	v_pk_add_f32 v[52:53], v[52:53], 1.0 op_sel_hi:[1,0]
	s_nop 0
	v_rcp_f32_e32 v52, v52
	v_rcp_f32_e32 v53, v53
	s_nop 0
	v_pk_mul_f32 v[44:45], v[50:51], v[52:53] op_sel_hi:[0,1]
	v_pk_mul_f32 v[40:41], v[40:41], v[44:45]
	v_pk_mul_f32 v[44:45], v[46:47], v[48:49] op_sel_hi:[1,0]
	v_cvt_pk_bf16_f32 v40, v40, v41
	v_exp_f32_e32 v44, v44
	v_exp_f32_e32 v45, v45
	s_nop 0
	v_pk_add_f32 v[44:45], v[44:45], 1.0 op_sel_hi:[1,0]
	s_nop 0
	v_rcp_f32_e32 v44, v44
	v_rcp_f32_e32 v45, v45
	s_nop 0
	v_pk_mul_f32 v[44:45], v[50:51], v[44:45] op_sel_hi:[0,1]
	v_pk_mul_f32 v[42:43], v[42:43], v[44:45]
	s_nop 0
	v_cvt_pk_bf16_f32 v41, v42, v43
	v_pk_mul_f32 v[42:43], v[36:37], v[48:49] op_sel_hi:[1,0]
	s_nop 0
	v_exp_f32_e32 v42, v42
	v_exp_f32_e32 v43, v43
	s_nop 0
	v_pk_add_f32 v[42:43], v[42:43], 1.0 op_sel_hi:[1,0]
	s_nop 0
	v_rcp_f32_e32 v42, v42
	v_rcp_f32_e32 v43, v43
	s_nop 0
	v_pk_mul_f32 v[36:37], v[50:51], v[42:43] op_sel_hi:[0,1]
	v_pk_mul_f32 v[32:33], v[32:33], v[36:37]
	s_nop 0
	v_cvt_pk_bf16_f32 v42, v32, v33
	v_pk_mul_f32 v[32:33], v[38:39], v[48:49] op_sel_hi:[1,0]
	s_nop 0
	v_exp_f32_e32 v32, v32
	v_exp_f32_e32 v33, v33
	s_nop 0
	v_pk_add_f32 v[32:33], v[32:33], 1.0 op_sel_hi:[1,0]
	s_nop 0
	v_rcp_f32_e32 v32, v32
	v_rcp_f32_e32 v33, v33
	s_nop 0
	v_pk_mul_f32 v[32:33], v[50:51], v[32:33] op_sel_hi:[0,1]
	v_pk_mul_f32 v[32:33], v[34:35], v[32:33]
	v_add_u32_e32 v35, 0xa0, v156
; __device__ __forceinline__ unsigned pk2(float lo, float hi) { const f32v2_t v = {lo, hi}; const bf16v2_t b = __builtin_convertvector(v, bf16v2_t); return __builtin_bit_cast(unsigned, b); }
; #define ST_OUT(p, v) __builtin_nontemporal_store((v), (p))
; #define PG8_BAR __builtin_amdgcn_s_barrier()
; template <class Epi, class Sched>
; __device__ __forceinline__ void gemm_phase(LAS unsigned char* lds, const Gemm g, const Sched& S, const Epi& E) {
;     ...
;         if (!has_next) break;
; #pragma unroll
;         for (int a = 0; a < 2; ++a)
; #pragma unroll
;             for (int b = 0; b < 2; ++b)
; #pragma unroll
;                 for (int m = 0; m < 4; ++m)
; #pragma unroll
;                     for (int n = 0; n < 2; ++n) acc[a][b][m][n] = (f32x4){0.f, 0.f, 0.f, 0.f};
;         cur = nxt; cA = nA; cB = nB; ++ui;
;         if (Sched::SEGMENTED) nt = S.nt(cur);
;     ...
;         if (wr == 1) PG8_BAR;
;     __device__ __forceinline__ void operator()(AccRef acc, const Unit& u, int wr, int wc, int fr, int fq) const {
;     ...
;             for (int m = 0; m < 4; ++m) {
;                 const int row = row0 + ai * HALF + m * 16;
;                 const float rinv = rsqrtf((float)rss[row] * (1.f / (16777216.f * DM)) + EPS);
;                 const float nrl = rinv * -1.4426950408889634f, r2 = rinv * rinv;
;                 unsigned ow[4];
; #pragma unroll
;                 for (int n = 0; n < 2; ++n)
; #pragma unroll
;                     for (int jp = 0; jp < 2; ++jp) {
;                         const f32v2_t ag = {acc[ai][0][m][n][2 * jp], acc[ai][0][m][n][2 * jp + 1]}, au = {acc[ai][1][m][n][2 * jp], acc[ai][1][m][n][2 * jp + 1]};
;                         const f32v2_t t = ag * nrl;
;                         f32v2_t e; e.x = __builtin_amdgcn_exp2f(t.x); e.y = __builtin_amdgcn_exp2f(t.y);
;                         const f32v2_t d = e + 1.0f;
;                         f32v2_t r; r.x = __builtin_amdgcn_rcpf(d.x); r.y = __builtin_amdgcn_rcpf(d.y);
;                         const f32v2_t hv = (ag * au) * (r * r2);
;                         ow[n * 2 + jp] = pk2(hv.x, hv.y);
;                     }
;                 u32x4 o; o.x = ow[0]; o.y = ow[1]; o.z = ow[2]; o.w = ow[3];
;                 ST_OUT((u32x4*)(H + (size_t)row * FF + col0), o);
	v_cvt_pk_bf16_f32 v43, v32, v33
	v_mad_i64_i32 v[32:33], s[22:23], v51, s6, v[112:113]
	v_lshl_add_u64 v[32:33], v[32:33], 0, v[114:115]
	global_store_dwordx4 v[32:33], v[40:43], off nt
	v_mov_b32_e32 v32, v216
	v_mov_b32_e32 v33, v217
	v_ffbh_u32_e32 v34, v33
	v_min_u32_e32 v34, 32, v34
	v_lshlrev_b64 v[32:33], v34, v[32:33]
	v_min_u32_e32 v32, 1, v32
	v_or_b32_e32 v32, v33, v32
	v_cvt_f32_u32_e32 v32, v32
	v_sub_u32_e32 v33, 32, v34
	v_ldexp_f32 v32, v32, v33
	v_fmamk_f32 v32, v32, 0x2e000000, v176
	v_cmp_gt_f32_e32 vcc, s7, v32
	v_mul_f32_e32 v33, 0x4b800000, v32
	s_nop 0
	v_cndmask_b32_e32 v32, v32, v33, vcc
	v_rsq_f32_e32 v32, v32
	s_nop 0
	v_mul_f32_e32 v33, 0x45800000, v32
	v_cndmask_b32_e32 v33, v32, v33, vcc
	v_mul_f32_e32 v32, 0xbfb8aa3b, v33
	v_pk_mul_f32 v[36:37], v[28:29], v[32:33] op_sel_hi:[1,0]
	v_mul_f32_e32 v34, v33, v33
	v_exp_f32_e32 v36, v36
	v_exp_f32_e32 v37, v37
	s_nop 0
	v_pk_add_f32 v[36:37], v[36:37], 1.0 op_sel_hi:[1,0]
	s_nop 0
	v_rcp_f32_e32 v36, v36
	v_rcp_f32_e32 v37, v37
	s_nop 0
	v_pk_mul_f32 v[28:29], v[34:35], v[36:37] op_sel_hi:[0,1]
	v_pk_mul_f32 v[24:25], v[24:25], v[28:29]
	v_pk_mul_f32 v[28:29], v[30:31], v[32:33] op_sel_hi:[1,0]
	v_cvt_pk_bf16_f32 v24, v24, v25
	v_exp_f32_e32 v28, v28
	v_exp_f32_e32 v29, v29
	s_nop 0
	v_pk_add_f32 v[28:29], v[28:29], 1.0 op_sel_hi:[1,0]
	s_nop 0
	v_rcp_f32_e32 v28, v28
	v_rcp_f32_e32 v29, v29
	s_nop 0
	v_pk_mul_f32 v[28:29], v[34:35], v[28:29] op_sel_hi:[0,1]
	v_pk_mul_f32 v[26:27], v[26:27], v[28:29]
	s_nop 0
	v_cvt_pk_bf16_f32 v25, v26, v27
	v_pk_mul_f32 v[26:27], v[20:21], v[32:33] op_sel_hi:[1,0]
	s_nop 0
	v_exp_f32_e32 v26, v26
	v_exp_f32_e32 v27, v27
	s_nop 0
	v_pk_add_f32 v[26:27], v[26:27], 1.0 op_sel_hi:[1,0]
	s_nop 0
	v_rcp_f32_e32 v26, v26
	v_rcp_f32_e32 v27, v27
	s_nop 0
	v_pk_mul_f32 v[20:21], v[34:35], v[26:27] op_sel_hi:[0,1]
	v_pk_mul_f32 v[16:17], v[16:17], v[20:21]
	s_nop 0
	v_cvt_pk_bf16_f32 v26, v16, v17
	v_pk_mul_f32 v[16:17], v[22:23], v[32:33] op_sel_hi:[1,0]
	s_nop 0
	v_exp_f32_e32 v16, v16
	v_exp_f32_e32 v17, v17
	s_nop 0
	v_pk_add_f32 v[16:17], v[16:17], 1.0 op_sel_hi:[1,0]
	s_nop 0
	v_rcp_f32_e32 v16, v16
	v_rcp_f32_e32 v17, v17
	s_nop 0
	v_pk_mul_f32 v[16:17], v[34:35], v[16:17] op_sel_hi:[0,1]
	v_pk_mul_f32 v[16:17], v[18:19], v[16:17]
	v_add_u32_e32 v19, 0xb0, v156
	v_cvt_pk_bf16_f32 v27, v16, v17
	v_mad_i64_i32 v[16:17], s[22:23], v35, s6, v[112:113]
	v_lshl_add_u64 v[16:17], v[16:17], 0, v[114:115]
	global_store_dwordx4 v[16:17], v[24:27], off nt
	v_mov_b32_e32 v16, v218
	v_mov_b32_e32 v17, v219
	v_ffbh_u32_e32 v18, v17
	v_min_u32_e32 v18, 32, v18
	v_lshlrev_b64 v[16:17], v18, v[16:17]
	v_min_u32_e32 v16, 1, v16
	v_or_b32_e32 v16, v17, v16
	v_cvt_f32_u32_e32 v16, v16
	v_sub_u32_e32 v17, 32, v18
	v_ldexp_f32 v16, v16, v17
	v_fmamk_f32 v16, v16, 0x2e000000, v176
	v_cmp_gt_f32_e32 vcc, s7, v16
	v_mul_f32_e32 v17, 0x4b800000, v16
	s_nop 0
	v_cndmask_b32_e32 v16, v16, v17, vcc
	v_rsq_f32_e32 v16, v16
	s_nop 0
	v_mul_f32_e32 v17, 0x45800000, v16
	v_cndmask_b32_e32 v17, v16, v17, vcc
	v_mul_f32_e32 v16, 0xbfb8aa3b, v17
	v_pk_mul_f32 v[20:21], v[12:13], v[16:17] op_sel_hi:[1,0]
	v_mul_f32_e32 v18, v17, v17
	v_exp_f32_e32 v20, v20
	v_exp_f32_e32 v21, v21
	s_andn2_b64 vcc, exec, s[38:39]
	v_pk_add_f32 v[20:21], v[20:21], 1.0 op_sel_hi:[1,0]
	s_nop 0
	v_rcp_f32_e32 v20, v20
	v_rcp_f32_e32 v21, v21
	s_nop 0
	v_pk_mul_f32 v[12:13], v[18:19], v[20:21] op_sel_hi:[0,1]
	v_pk_mul_f32 v[8:9], v[8:9], v[12:13]
	v_pk_mul_f32 v[12:13], v[14:15], v[16:17] op_sel_hi:[1,0]
	v_cvt_pk_bf16_f32 v8, v8, v9
	v_exp_f32_e32 v12, v12
	v_exp_f32_e32 v13, v13
	s_nop 0
	v_pk_add_f32 v[12:13], v[12:13], 1.0 op_sel_hi:[1,0]
	s_nop 0
	v_rcp_f32_e32 v12, v12
	v_rcp_f32_e32 v13, v13
	s_nop 0
	v_pk_mul_f32 v[12:13], v[18:19], v[12:13] op_sel_hi:[0,1]
	v_pk_mul_f32 v[10:11], v[10:11], v[12:13]
	s_nop 0
	v_cvt_pk_bf16_f32 v9, v10, v11
	v_pk_mul_f32 v[10:11], v[4:5], v[16:17] op_sel_hi:[1,0]
	s_nop 0
	v_exp_f32_e32 v10, v10
	v_exp_f32_e32 v11, v11
	s_nop 0
	v_pk_add_f32 v[10:11], v[10:11], 1.0 op_sel_hi:[1,0]
	s_nop 0
	v_rcp_f32_e32 v10, v10
	v_rcp_f32_e32 v11, v11
	s_nop 0
	v_pk_mul_f32 v[4:5], v[18:19], v[10:11] op_sel_hi:[0,1]
	v_pk_mul_f32 v[0:1], v[0:1], v[4:5]
	s_nop 0
	v_cvt_pk_bf16_f32 v10, v0, v1
	v_pk_mul_f32 v[0:1], v[6:7], v[16:17] op_sel_hi:[1,0]
	s_nop 0
	v_exp_f32_e32 v0, v0
	v_exp_f32_e32 v1, v1
	s_nop 0
	v_pk_add_f32 v[0:1], v[0:1], 1.0 op_sel_hi:[1,0]
	s_nop 0
	v_rcp_f32_e32 v0, v0
	v_rcp_f32_e32 v1, v1
	s_nop 0
	v_pk_mul_f32 v[0:1], v[18:19], v[0:1] op_sel_hi:[0,1]
	v_pk_mul_f32 v[0:1], v[2:3], v[0:1]
	s_nop 0
	v_cvt_pk_bf16_f32 v11, v0, v1
	v_mad_i64_i32 v[0:1], s[22:23], v19, s6, v[112:113]
	v_lshl_add_u64 v[0:1], v[0:1], 0, v[114:115]
	s_mov_b64 s[22:23], -1
	global_store_dwordx4 v[0:1], v[8:11], off nt
	s_cbranch_vccnz .LBB0_741
	s_andn2_b64 vcc, exec, s[0:1]
	s_cbranch_vccnz .LBB0_740
	s_barrier
	s_branch .LBB0_740

; __device__ __forceinline__ unsigned pk2(float lo, float hi) { const f32v2_t v = {lo, hi}; const bf16v2_t b = __builtin_convertvector(v, bf16v2_t); return __builtin_bit_cast(unsigned, b); }
; #define LD_W(p) __builtin_nontemporal_load(p)
; __device__ __forceinline__ void tr_item(const float* W, int ldw, int col0, const float* ksc, bf16_t* WT, int ldt, int drow, int k0, int n0, unsigned* scr, int lane) {
;     ...
;     for (int m = 0; m < 8; ++m) { v[2 * m] = LD_W((const f32x4*)(src + (size_t)(8 * m) * ldw)); v[2 * m + 1] = LD_W((const f32x4*)(src + (size_t)(8 * m + 1) * ldw)); }
; #pragma unroll
;     for (int m = 0; m < 8; ++m) {
;         const float s0 = ksc ? ksc[k0 + 8 * m + 2 * b] : 1.f, s1 = ksc ? ksc[k0 + 8 * m + 2 * b + 1] : 1.f;
; #pragma unroll
;         for (int e = 0; e < 4; ++e) scr[(4 * a + e) * 32 + (((m ^ (a & 7)) << 2) | b)] = pk2(v[2 * m][e] * s0, v[2 * m + 1][e] * s1);
.LBB0_763:
	s_and_b64 vcc, exec, s[38:39]
	s_cbranch_vccnz .LBB0_765
	global_load_dword v97, v[94:95], off offset:4
	global_load_dword v200, v[94:95], off offset:32
	global_load_dword v201, v[94:95], off offset:36
	global_load_dword v202, v[94:95], off offset:64
	global_load_dword v203, v[94:95], off offset:68
	global_load_dword v204, v[94:95], off offset:96
	global_load_dword v205, v[94:95], off offset:100
	global_load_dword v206, v[94:95], off offset:128
	global_load_dword v207, v[94:95], off offset:132
	global_load_dword v208, v[94:95], off offset:160
	global_load_dword v209, v[94:95], off offset:164
	global_load_dword v210, v[94:95], off offset:192
	global_load_dword v211, v[94:95], off offset:196
	global_load_dword v212, v[94:95], off offset:224
	global_load_dword v213, v[94:95], off offset:228
.LBB0_765:
	s_waitcnt vmcnt(15)
	v_mov_b32_e32 v130, v56
	s_waitcnt vmcnt(14)
	v_mov_b32_e32 v131, v60
	v_mov_b32_e32 v60, v57
	s_waitcnt vmcnt(0)
	v_pk_mul_f32 v[130:131], v[130:131], v[96:97]
	v_pk_mul_f32 v[56:57], v[60:61], v[96:97]
	v_cvt_pk_bf16_f32 v93, v130, v131
	v_cvt_pk_bf16_f32 v56, v56, v57
	ds_write2_b32 v89, v93, v56 offset1:32
	v_mov_b32_e32 v56, v58
	v_mov_b32_e32 v57, v62
	v_pk_mul_f32 v[56:57], v[56:57], v[96:97]
	v_mov_b32_e32 v62, v59
	v_cvt_pk_bf16_f32 v58, v56, v57
	v_pk_mul_f32 v[56:57], v[62:63], v[96:97]
	s_and_b64 vcc, exec, s[38:39]
	v_cvt_pk_bf16_f32 v56, v56, v57
	ds_write2_b32 v89, v58, v56 offset0:64 offset1:96
	v_mov_b32_e32 v57, 1.0
	v_mov_b32_e32 v56, 1.0
	s_cbranch_vccnz .LBB0_767
	v_mov_b32_e32 v56, v200
.LBB0_767:
	s_and_b64 vcc, exec, s[38:39]
	s_cbranch_vccnz .LBB0_769
	v_mov_b32_e32 v57, v201
.LBB0_769:
	v_mov_b32_e32 v58, v48
	v_mov_b32_e32 v59, v52
	s_waitcnt vmcnt(0)
	v_pk_mul_f32 v[58:59], v[58:59], v[56:57]
	v_mov_b32_e32 v52, v49
	v_cvt_pk_bf16_f32 v48, v58, v59
	ds_write_b32 v98, v48
	v_pk_mul_f32 v[48:49], v[52:53], v[56:57]
	s_and_b64 vcc, exec, s[38:39]
	v_cvt_pk_bf16_f32 v52, v48, v49
	v_mov_b32_e32 v48, v50
	v_mov_b32_e32 v49, v54
	v_pk_mul_f32 v[48:49], v[48:49], v[56:57]
	v_mov_b32_e32 v54, v51
	v_cvt_pk_bf16_f32 v48, v48, v49
	ds_write2_b32 v99, v52, v48 offset0:32 offset1:64
	v_pk_mul_f32 v[48:49], v[54:55], v[56:57]
	s_nop 0
	v_cvt_pk_bf16_f32 v48, v48, v49
	ds_write_b32 v99, v48 offset:384
	v_mov_b32_e32 v49, 1.0
	v_mov_b32_e32 v48, 1.0
	s_cbranch_vccnz .LBB0_771
	v_mov_b32_e32 v48, v202
.LBB0_771:
	s_and_b64 vcc, exec, s[38:39]
	s_cbranch_vccnz .LBB0_773
	v_mov_b32_e32 v49, v203
.LBB0_773:
	v_mov_b32_e32 v50, v40
	v_mov_b32_e32 v51, v44
	s_waitcnt vmcnt(0)
	v_pk_mul_f32 v[50:51], v[50:51], v[48:49]
	v_mov_b32_e32 v44, v41
	v_cvt_pk_bf16_f32 v40, v50, v51
	ds_write_b32 v100, v40
	v_pk_mul_f32 v[40:41], v[44:45], v[48:49]
	s_and_b64 vcc, exec, s[38:39]
	v_cvt_pk_bf16_f32 v44, v40, v41
	v_mov_b32_e32 v40, v42
	v_mov_b32_e32 v41, v46
	v_pk_mul_f32 v[40:41], v[40:41], v[48:49]
	v_mov_b32_e32 v46, v43
	v_cvt_pk_bf16_f32 v40, v40, v41
	ds_write2_b32 v101, v44, v40 offset0:32 offset1:64
	v_pk_mul_f32 v[40:41], v[46:47], v[48:49]
	s_nop 0
	v_cvt_pk_bf16_f32 v40, v40, v41
	ds_write_b32 v101, v40 offset:384
	v_mov_b32_e32 v41, 1.0
	v_mov_b32_e32 v40, 1.0
	s_cbranch_vccnz .LBB0_775
	v_mov_b32_e32 v40, v204
.LBB0_775:
	s_and_b64 vcc, exec, s[38:39]
	s_cbranch_vccnz .LBB0_777
	v_mov_b32_e32 v41, v205
.LBB0_777:
	v_mov_b32_e32 v42, v32
	v_mov_b32_e32 v43, v36
	s_waitcnt vmcnt(0)
	v_pk_mul_f32 v[42:43], v[42:43], v[40:41]
	v_mov_b32_e32 v36, v33
	v_cvt_pk_bf16_f32 v32, v42, v43
	ds_write_b32 v102, v32
	v_pk_mul_f32 v[32:33], v[36:37], v[40:41]
	s_and_b64 vcc, exec, s[38:39]
	v_cvt_pk_bf16_f32 v36, v32, v33
	v_mov_b32_e32 v32, v34
	v_mov_b32_e32 v33, v38
	v_pk_mul_f32 v[32:33], v[32:33], v[40:41]
	v_mov_b32_e32 v38, v35
	v_cvt_pk_bf16_f32 v32, v32, v33
	ds_write2_b32 v103, v36, v32 offset0:32 offset1:64
	v_pk_mul_f32 v[32:33], v[38:39], v[40:41]
	s_nop 0
	v_cvt_pk_bf16_f32 v32, v32, v33
	ds_write_b32 v103, v32 offset:384
	v_mov_b32_e32 v33, 1.0
	v_mov_b32_e32 v32, 1.0
	s_cbranch_vccnz .LBB0_779
	v_mov_b32_e32 v32, v206
.LBB0_779:
	s_and_b64 vcc, exec, s[38:39]
	s_cbranch_vccnz .LBB0_781
	v_mov_b32_e32 v33, v207
.LBB0_781:
	v_mov_b32_e32 v34, v24
	v_mov_b32_e32 v35, v28
	s_waitcnt vmcnt(0)
	v_pk_mul_f32 v[34:35], v[34:35], v[32:33]
	v_mov_b32_e32 v28, v25
	v_cvt_pk_bf16_f32 v24, v34, v35
	ds_write_b32 v104, v24
	v_pk_mul_f32 v[24:25], v[28:29], v[32:33]
	s_and_b64 vcc, exec, s[38:39]
	v_cvt_pk_bf16_f32 v28, v24, v25
	v_mov_b32_e32 v24, v26
	v_mov_b32_e32 v25, v30
	v_pk_mul_f32 v[24:25], v[24:25], v[32:33]
	v_mov_b32_e32 v30, v27
	v_cvt_pk_bf16_f32 v24, v24, v25
	ds_write2_b32 v105, v28, v24 offset0:32 offset1:64
	v_pk_mul_f32 v[24:25], v[30:31], v[32:33]
	s_nop 0
	v_cvt_pk_bf16_f32 v24, v24, v25
	ds_write_b32 v105, v24 offset:384
	v_mov_b32_e32 v25, 1.0
	v_mov_b32_e32 v24, 1.0
	s_cbranch_vccnz .LBB0_783
	v_mov_b32_e32 v24, v208
.LBB0_783:
	s_and_b64 vcc, exec, s[38:39]
	s_cbranch_vccnz .LBB0_785
	v_mov_b32_e32 v25, v209
.LBB0_785:
	v_mov_b32_e32 v26, v16
	v_mov_b32_e32 v27, v20
	s_waitcnt vmcnt(0)
	v_pk_mul_f32 v[26:27], v[26:27], v[24:25]
	v_mov_b32_e32 v20, v17
	v_cvt_pk_bf16_f32 v16, v26, v27
	ds_write_b32 v106, v16
	v_pk_mul_f32 v[16:17], v[20:21], v[24:25]
	s_and_b64 vcc, exec, s[38:39]
	v_cvt_pk_bf16_f32 v20, v16, v17
	v_mov_b32_e32 v16, v18
	v_mov_b32_e32 v17, v22
	v_pk_mul_f32 v[16:17], v[16:17], v[24:25]
	v_mov_b32_e32 v22, v19
	v_cvt_pk_bf16_f32 v16, v16, v17
	ds_write2_b32 v107, v20, v16 offset0:32 offset1:64
	v_pk_mul_f32 v[16:17], v[22:23], v[24:25]
	s_nop 0
	v_cvt_pk_bf16_f32 v16, v16, v17
	ds_write_b32 v107, v16 offset:384
	v_mov_b32_e32 v17, 1.0
	v_mov_b32_e32 v16, 1.0
	s_cbranch_vccnz .LBB0_787
	v_mov_b32_e32 v16, v210
.LBB0_787:
	s_and_b64 vcc, exec, s[38:39]
	s_cbranch_vccnz .LBB0_789
	v_mov_b32_e32 v17, v211
.LBB0_789:
	v_mov_b32_e32 v18, v8
	v_mov_b32_e32 v19, v12
	s_waitcnt vmcnt(0)
	v_pk_mul_f32 v[18:19], v[18:19], v[16:17]
	v_mov_b32_e32 v12, v9
	v_cvt_pk_bf16_f32 v8, v18, v19
	ds_write_b32 v108, v8
	v_pk_mul_f32 v[8:9], v[12:13], v[16:17]
	s_and_b64 vcc, exec, s[38:39]
	v_cvt_pk_bf16_f32 v12, v8, v9
	v_mov_b32_e32 v8, v10
	v_mov_b32_e32 v9, v14
	v_pk_mul_f32 v[8:9], v[8:9], v[16:17]
	v_mov_b32_e32 v14, v11
	v_cvt_pk_bf16_f32 v8, v8, v9
	ds_write2_b32 v109, v12, v8 offset0:32 offset1:64
	v_pk_mul_f32 v[8:9], v[14:15], v[16:17]
	s_nop 0
	v_cvt_pk_bf16_f32 v8, v8, v9
	ds_write_b32 v109, v8 offset:384
	v_mov_b32_e32 v9, 1.0
	v_mov_b32_e32 v8, 1.0
	s_cbranch_vccnz .LBB0_791
	v_mov_b32_e32 v8, v212
.LBB0_791:
	s_and_b64 vcc, exec, s[38:39]
	s_cbranch_vccnz .LBB0_793
	v_mov_b32_e32 v9, v213

; __device__ __forceinline__ unsigned pk2(float lo, float hi) { const f32v2_t v = {lo, hi}; const bf16v2_t b = __builtin_convertvector(v, bf16v2_t); return __builtin_bit_cast(unsigned, b); }
; __device__ __forceinline__ void tr_item(const float* W, int ldw, int col0, const float* ksc, bf16_t* WT, int ldt, int drow, int k0, int n0, unsigned* scr, int lane) {
;     ...
;     for (int m = 0; m < 8; ++m) {
;         const float s0 = ksc ? ksc[k0 + 8 * m + 2 * b] : 1.f, s1 = ksc ? ksc[k0 + 8 * m + 2 * b + 1] : 1.f;
; #pragma unroll
;         for (int e = 0; e < 4; ++e) scr[(4 * a + e) * 32 + (((m ^ (a & 7)) << 2) | b)] = pk2(v[2 * m][e] * s0, v[2 * m + 1][e] * s1);
.LBB0_923:
	s_waitcnt vmcnt(15)
	v_mov_b32_e32 v130, v56
	s_waitcnt vmcnt(14)
	v_mov_b32_e32 v131, v60
	v_mov_b32_e32 v60, v57
	s_waitcnt vmcnt(0)
	v_pk_mul_f32 v[130:131], v[130:131], v[96:97]
	v_pk_mul_f32 v[56:57], v[60:61], v[96:97]
	v_cvt_pk_bf16_f32 v91, v130, v131
	v_cvt_pk_bf16_f32 v56, v56, v57
	ds_write2_b32 v89, v91, v56 offset1:32
	v_mov_b32_e32 v56, v58
	v_mov_b32_e32 v57, v62
	v_pk_mul_f32 v[56:57], v[56:57], v[96:97]
	v_mov_b32_e32 v62, v59
	v_cvt_pk_bf16_f32 v58, v56, v57
	v_pk_mul_f32 v[56:57], v[62:63], v[96:97]
	s_and_b64 vcc, exec, s[38:39]
	v_cvt_pk_bf16_f32 v56, v56, v57
	ds_write2_b32 v89, v58, v56 offset0:64 offset1:96
	v_mov_b32_e32 v57, 1.0
	v_mov_b32_e32 v56, 1.0
	s_cbranch_vccnz .LBB0_925
	v_mov_b32_e32 v56, v200
